# all 16 weight-transpose inner loops (f32->bf16 weight conversion) now keep 32 nontemporal row loads in flight per wave instead of 8 (or ~1); arithmetic unchanged
# baseline (speedup 1.0000x reference)
.LBB0_11:
	s_cmpk_gt_i32 s27, 0xaff
	s_mov_b64 s[4:5], -1
	s_cbranch_scc0 .LBB0_15
	s_lshl_b32 s4, s22, 2
	s_and_b32 s14, s24, 0x1ffc0
	s_and_b32 s10, s4, 0xf80
	v_or_b32_e32 v12, s14, v41
	v_lshl_or_b32 v14, v12, 12, s10
	v_or_b32_e32 v12, s14, v42
	v_lshl_or_b32 v16, v12, 12, s10
	v_or_b32_e32 v12, s14, v43
	s_load_dwordx2 s[4:5], s[0:1], 0x20
	v_lshl_or_b32 v18, v12, 12, s10
	v_or_b32_e32 v12, s14, v44
	v_lshl_or_b32 v20, v12, 12, s10
	v_or_b32_e32 v12, s14, v45
	v_lshl_or_b32 v22, v12, 12, s10
	v_or_b32_e32 v12, s14, v46
	v_or_b32_e32 v4, s14, v40
	v_lshl_or_b32 v24, v12, 12, s10
	v_or_b32_e32 v12, s14, v2
	v_lshl_or_b32 v4, v4, 12, s10
	v_mov_b32_e32 v15, v5
	v_mov_b32_e32 v17, v5
	v_mov_b32_e32 v19, v5
	v_mov_b32_e32 v21, v5
	v_mov_b32_e32 v23, v5
	v_mov_b32_e32 v25, v5
	v_lshl_or_b32 v26, v12, 12, s10
	v_mov_b32_e32 v27, v5
	s_waitcnt lgkmcnt(0)
	v_lshl_add_u64 v[28:29], s[4:5], 0, v[10:11]
	v_lshl_add_u64 v[12:13], v[28:29], 0, v[4:5]
	v_lshl_add_u64 v[14:15], v[28:29], 0, v[14:15]
	v_lshl_add_u64 v[16:17], v[28:29], 0, v[16:17]
	v_lshl_add_u64 v[18:19], v[28:29], 0, v[18:19]
	v_lshl_add_u64 v[20:21], v[28:29], 0, v[20:21]
	v_lshl_add_u64 v[22:23], v[28:29], 0, v[22:23]
	v_lshl_add_u64 v[24:25], v[28:29], 0, v[24:25]
	v_lshl_add_u64 v[26:27], v[28:29], 0, v[26:27]
	s_mov_b64 s[4:5], 0
	v_mov_b32_e32 v4, v39
	v_mov_b32_e32 v230, v26
	v_mov_b32_e32 v231, v27
	v_mov_b32_e32 v234, v4
	s_mov_b32 s50, 0x2000
	s_mov_b32 s51, 0
	global_load_dword v180, v[230:231], off nt
	v_lshl_add_u64 v[230:231], v[230:231], 0, s[50:51]
	global_load_dword v181, v[230:231], off nt
	v_lshl_add_u64 v[230:231], v[230:231], 0, s[50:51]
	global_load_dword v182, v[230:231], off nt
	v_lshl_add_u64 v[230:231], v[230:231], 0, s[50:51]
	global_load_dword v183, v[230:231], off nt
	v_lshl_add_u64 v[230:231], v[230:231], 0, s[50:51]
	global_load_dword v184, v[230:231], off nt
	v_lshl_add_u64 v[230:231], v[230:231], 0, s[50:51]
	global_load_dword v185, v[230:231], off nt
	v_lshl_add_u64 v[230:231], v[230:231], 0, s[50:51]
	global_load_dword v186, v[230:231], off nt
	v_lshl_add_u64 v[230:231], v[230:231], 0, s[50:51]
	global_load_dword v187, v[230:231], off nt
	v_lshl_add_u64 v[230:231], v[230:231], 0, s[50:51]
	global_load_dword v188, v[230:231], off nt
	v_lshl_add_u64 v[230:231], v[230:231], 0, s[50:51]
	global_load_dword v189, v[230:231], off nt
	v_lshl_add_u64 v[230:231], v[230:231], 0, s[50:51]
	global_load_dword v190, v[230:231], off nt
	v_lshl_add_u64 v[230:231], v[230:231], 0, s[50:51]
	global_load_dword v191, v[230:231], off nt
	v_lshl_add_u64 v[230:231], v[230:231], 0, s[50:51]
	global_load_dword v192, v[230:231], off nt
	v_lshl_add_u64 v[230:231], v[230:231], 0, s[50:51]
	global_load_dword v193, v[230:231], off nt
	v_lshl_add_u64 v[230:231], v[230:231], 0, s[50:51]
	global_load_dword v194, v[230:231], off nt
	v_lshl_add_u64 v[230:231], v[230:231], 0, s[50:51]
	global_load_dword v195, v[230:231], off nt
	v_lshl_add_u64 v[230:231], v[230:231], 0, s[50:51]
	global_load_dword v196, v[230:231], off nt
	v_lshl_add_u64 v[230:231], v[230:231], 0, s[50:51]
	global_load_dword v197, v[230:231], off nt
	v_lshl_add_u64 v[230:231], v[230:231], 0, s[50:51]
	global_load_dword v198, v[230:231], off nt
	v_lshl_add_u64 v[230:231], v[230:231], 0, s[50:51]
	global_load_dword v199, v[230:231], off nt
	v_lshl_add_u64 v[230:231], v[230:231], 0, s[50:51]
	global_load_dword v200, v[230:231], off nt
	v_lshl_add_u64 v[230:231], v[230:231], 0, s[50:51]
	global_load_dword v201, v[230:231], off nt
	v_lshl_add_u64 v[230:231], v[230:231], 0, s[50:51]
	global_load_dword v202, v[230:231], off nt
	v_lshl_add_u64 v[230:231], v[230:231], 0, s[50:51]
	global_load_dword v203, v[230:231], off nt
	v_lshl_add_u64 v[230:231], v[230:231], 0, s[50:51]
	global_load_dword v204, v[230:231], off nt
	v_lshl_add_u64 v[230:231], v[230:231], 0, s[50:51]
	global_load_dword v205, v[230:231], off nt
	v_lshl_add_u64 v[230:231], v[230:231], 0, s[50:51]
	global_load_dword v206, v[230:231], off nt
	v_lshl_add_u64 v[230:231], v[230:231], 0, s[50:51]
	global_load_dword v207, v[230:231], off nt
	v_lshl_add_u64 v[230:231], v[230:231], 0, s[50:51]
	global_load_dword v208, v[230:231], off nt
	v_lshl_add_u64 v[230:231], v[230:231], 0, s[50:51]
	global_load_dword v209, v[230:231], off nt
	v_lshl_add_u64 v[230:231], v[230:231], 0, s[50:51]
	global_load_dword v210, v[230:231], off nt
	v_lshl_add_u64 v[230:231], v[230:231], 0, s[50:51]
	global_load_dword v211, v[230:231], off nt
	s_waitcnt vmcnt(31)
	ds_write_b32 v234, v180
	s_waitcnt vmcnt(30)
	ds_write_b32 v234, v181 offset:264
	s_waitcnt vmcnt(29)
	ds_write_b32 v234, v182 offset:528
	s_waitcnt vmcnt(28)
	ds_write_b32 v234, v183 offset:792
	s_waitcnt vmcnt(27)
	ds_write_b32 v234, v184 offset:1056
	s_waitcnt vmcnt(26)
	ds_write_b32 v234, v185 offset:1320
	s_waitcnt vmcnt(25)
	ds_write_b32 v234, v186 offset:1584
	s_waitcnt vmcnt(24)
	ds_write_b32 v234, v187 offset:1848
	s_waitcnt vmcnt(23)
	ds_write_b32 v234, v188 offset:2112
	s_waitcnt vmcnt(22)
	ds_write_b32 v234, v189 offset:2376
	s_waitcnt vmcnt(21)
	ds_write_b32 v234, v190 offset:2640
	s_waitcnt vmcnt(20)
	ds_write_b32 v234, v191 offset:2904
	s_waitcnt vmcnt(19)
	ds_write_b32 v234, v192 offset:3168
	s_waitcnt vmcnt(18)
	ds_write_b32 v234, v193 offset:3432
	s_waitcnt vmcnt(17)
	ds_write_b32 v234, v194 offset:3696
	s_waitcnt vmcnt(16)
	ds_write_b32 v234, v195 offset:3960
	s_waitcnt vmcnt(15)
	ds_write_b32 v234, v196 offset:4224
	s_waitcnt vmcnt(14)
	ds_write_b32 v234, v197 offset:4488
	s_waitcnt vmcnt(13)
	ds_write_b32 v234, v198 offset:4752
	s_waitcnt vmcnt(12)
	ds_write_b32 v234, v199 offset:5016
	s_waitcnt vmcnt(11)
	ds_write_b32 v234, v200 offset:5280
	s_waitcnt vmcnt(10)
	ds_write_b32 v234, v201 offset:5544
	s_waitcnt vmcnt(9)
	ds_write_b32 v234, v202 offset:5808
	s_waitcnt vmcnt(8)
	ds_write_b32 v234, v203 offset:6072
	s_waitcnt vmcnt(7)
	ds_write_b32 v234, v204 offset:6336
	s_waitcnt vmcnt(6)
	ds_write_b32 v234, v205 offset:6600
	s_waitcnt vmcnt(5)
	ds_write_b32 v234, v206 offset:6864
	s_waitcnt vmcnt(4)
	ds_write_b32 v234, v207 offset:7128
	s_waitcnt vmcnt(3)
	ds_write_b32 v234, v208 offset:7392
	s_waitcnt vmcnt(2)
	ds_write_b32 v234, v209 offset:7656
	s_waitcnt vmcnt(1)
	ds_write_b32 v234, v210 offset:7920
	s_waitcnt vmcnt(0)
	ds_write_b32 v234, v211 offset:8184
	s_mov_b32 s4, 0x40000
	v_add_u32_e32 v4, 0x2100, v4
	s_waitcnt lgkmcnt(0)
	s_lshl_b32 s4, s27, 1
	s_lshl_b32 s5, s27, 5
	s_add_i32 s4, s4, 0x1ea00
	s_and_b32 s5, s5, 0x3e0
	ds_read2_b32 v[16:17], v35 offset0:33 offset1:41
	ds_read2_b32 v[18:19], v35 offset1:8
	ds_read2_b32 v[20:21], v35 offset0:66 offset1:74
	ds_read2_b32 v[22:23], v35 offset0:99 offset1:107
	ds_read2_b32 v[24:25], v35 offset0:132 offset1:140
	ds_read2_b32 v[26:27], v35 offset0:165 offset1:173
	ds_read2_b32 v[28:29], v35 offset0:198 offset1:206
	ds_read2_b32 v[30:31], v35 offset0:231 offset1:239
	s_and_b32 s4, s4, 0x1ffc0
	v_or_b32_e32 v4, s5, v3
	s_lshl_b32 s10, s4, 1
	v_mul_u32_u24_e32 v4, 0xb00, v4
	v_lshl_add_u64 v[32:33], v[8:9], 0, s[10:11]
	v_lshlrev_b32_e32 v4, 1, v4
	v_lshl_add_u64 v[48:49], v[32:33], 0, v[4:5]
	v_or_b32_e32 v4, s5, v36
	s_waitcnt lgkmcnt(6)
	v_cvt_pk_bf16_f32 v12, v18, v16
	s_waitcnt lgkmcnt(4)
	v_cvt_pk_bf16_f32 v13, v20, v22
	s_waitcnt lgkmcnt(2)
	v_cvt_pk_bf16_f32 v14, v24, v26
	s_waitcnt lgkmcnt(0)
	v_cvt_pk_bf16_f32 v15, v28, v30
	v_mul_u32_u24_e32 v4, 0xb00, v4
	global_store_dwordx4 v[48:49], v[12:15], off
	v_lshlrev_b32_e32 v4, 1, v4
	s_nop 0
	v_cvt_pk_bf16_f32 v12, v19, v17
	v_cvt_pk_bf16_f32 v13, v21, v23
	v_cvt_pk_bf16_f32 v14, v25, v27
	v_cvt_pk_bf16_f32 v15, v29, v31
	v_lshl_add_u64 v[16:17], v[32:33], 0, v[4:5]
	ds_read2_b32 v[18:19], v35 offset0:16 offset1:24
	ds_read2_b32 v[20:21], v35 offset0:49 offset1:57
	ds_read2_b32 v[22:23], v35 offset0:82 offset1:90
	ds_read2_b32 v[24:25], v35 offset0:115 offset1:123
	ds_read2_b32 v[26:27], v35 offset0:148 offset1:156
	ds_read2_b32 v[28:29], v35 offset0:181 offset1:189
	ds_read2_b32 v[30:31], v35 offset0:214 offset1:222
	ds_read2_b32 v[48:49], v35 offset0:247 offset1:255
	v_or_b32_e32 v4, s5, v37
	v_mul_u32_u24_e32 v4, 0xb00, v4
	v_lshlrev_b32_e32 v4, 1, v4
	global_store_dwordx4 v[16:17], v[12:15], off
	v_lshl_add_u64 v[16:17], v[32:33], 0, v[4:5]
	v_or_b32_e32 v4, s5, v38
	v_mul_u32_u24_e32 v4, 0xb00, v4
	s_waitcnt lgkmcnt(6)
	v_cvt_pk_bf16_f32 v12, v18, v20
	s_waitcnt lgkmcnt(4)
	v_cvt_pk_bf16_f32 v13, v22, v24
	s_waitcnt lgkmcnt(2)
	v_cvt_pk_bf16_f32 v14, v26, v28
	s_waitcnt lgkmcnt(0)
	v_cvt_pk_bf16_f32 v15, v30, v48
	v_lshlrev_b32_e32 v4, 1, v4
	global_store_dwordx4 v[16:17], v[12:15], off
	v_lshl_add_u64 v[16:17], v[32:33], 0, v[4:5]
	s_mov_b64 s[4:5], 0
	v_cvt_pk_bf16_f32 v12, v19, v21
	v_cvt_pk_bf16_f32 v13, v23, v25
	v_cvt_pk_bf16_f32 v14, v27, v29
	v_cvt_pk_bf16_f32 v15, v31, v49
	global_store_dwordx4 v[16:17], v[12:15], off
	s_waitcnt lgkmcnt(0)

.LBB0_516:
	s_ashr_i32 s0, s6, 31
	s_lshr_b32 s0, s0, 27
	s_add_i32 s0, s6, s0
	s_and_b32 s1, s0, 0x7ffffe0
	s_sub_i32 s1, s6, s1
	s_lshl_b32 s0, s0, 1
	s_and_b32 s4, s0, 0xffffffc0
	s_lshl_b32 s0, s1, 5
	s_ashr_i32 s1, s0, 31
	v_lshl_add_u64 v[4:5], s[0:1], 2, v[0:1]
	v_or_b32_e32 v13, s4, v6
	v_mov_b32_e32 v14, v12
	s_mov_b32 s1, 0
	v_mov_b32_e32 v230, v13
	v_mov_b32_e32 v231, 0
	v_lshlrev_b64 v[230:231], 12, v[230:231]
	v_lshl_add_u64 v[230:231], v[4:5], 0, v[230:231]
	v_mov_b32_e32 v234, v14
	s_mov_b32 s50, 0x2000
	s_mov_b32 s51, 0
	global_load_dword v150, v[230:231], off nt
	v_lshl_add_u64 v[230:231], v[230:231], 0, s[50:51]
	global_load_dword v151, v[230:231], off nt
	v_lshl_add_u64 v[230:231], v[230:231], 0, s[50:51]
	global_load_dword v152, v[230:231], off nt
	v_lshl_add_u64 v[230:231], v[230:231], 0, s[50:51]
	global_load_dword v153, v[230:231], off nt
	v_lshl_add_u64 v[230:231], v[230:231], 0, s[50:51]
	global_load_dword v154, v[230:231], off nt
	v_lshl_add_u64 v[230:231], v[230:231], 0, s[50:51]
	global_load_dword v155, v[230:231], off nt
	v_lshl_add_u64 v[230:231], v[230:231], 0, s[50:51]
	global_load_dword v156, v[230:231], off nt
	v_lshl_add_u64 v[230:231], v[230:231], 0, s[50:51]
	global_load_dword v157, v[230:231], off nt
	v_lshl_add_u64 v[230:231], v[230:231], 0, s[50:51]
	global_load_dword v158, v[230:231], off nt
	v_lshl_add_u64 v[230:231], v[230:231], 0, s[50:51]
	global_load_dword v159, v[230:231], off nt
	v_lshl_add_u64 v[230:231], v[230:231], 0, s[50:51]
	global_load_dword v160, v[230:231], off nt
	v_lshl_add_u64 v[230:231], v[230:231], 0, s[50:51]
	global_load_dword v161, v[230:231], off nt
	v_lshl_add_u64 v[230:231], v[230:231], 0, s[50:51]
	global_load_dword v162, v[230:231], off nt
	v_lshl_add_u64 v[230:231], v[230:231], 0, s[50:51]
	global_load_dword v163, v[230:231], off nt
	v_lshl_add_u64 v[230:231], v[230:231], 0, s[50:51]
	global_load_dword v164, v[230:231], off nt
	v_lshl_add_u64 v[230:231], v[230:231], 0, s[50:51]
	global_load_dword v165, v[230:231], off nt
	v_lshl_add_u64 v[230:231], v[230:231], 0, s[50:51]
	global_load_dword v166, v[230:231], off nt
	v_lshl_add_u64 v[230:231], v[230:231], 0, s[50:51]
	global_load_dword v167, v[230:231], off nt
	v_lshl_add_u64 v[230:231], v[230:231], 0, s[50:51]
	global_load_dword v168, v[230:231], off nt
	v_lshl_add_u64 v[230:231], v[230:231], 0, s[50:51]
	global_load_dword v169, v[230:231], off nt
	v_lshl_add_u64 v[230:231], v[230:231], 0, s[50:51]
	global_load_dword v170, v[230:231], off nt
	v_lshl_add_u64 v[230:231], v[230:231], 0, s[50:51]
	global_load_dword v171, v[230:231], off nt
	v_lshl_add_u64 v[230:231], v[230:231], 0, s[50:51]
	global_load_dword v172, v[230:231], off nt
	v_lshl_add_u64 v[230:231], v[230:231], 0, s[50:51]
	global_load_dword v173, v[230:231], off nt
	v_lshl_add_u64 v[230:231], v[230:231], 0, s[50:51]
	global_load_dword v174, v[230:231], off nt
	v_lshl_add_u64 v[230:231], v[230:231], 0, s[50:51]
	global_load_dword v175, v[230:231], off nt
	v_lshl_add_u64 v[230:231], v[230:231], 0, s[50:51]
	global_load_dword v176, v[230:231], off nt
	v_lshl_add_u64 v[230:231], v[230:231], 0, s[50:51]
	global_load_dword v177, v[230:231], off nt
	v_lshl_add_u64 v[230:231], v[230:231], 0, s[50:51]
	global_load_dword v178, v[230:231], off nt
	v_lshl_add_u64 v[230:231], v[230:231], 0, s[50:51]
	global_load_dword v179, v[230:231], off nt
	v_lshl_add_u64 v[230:231], v[230:231], 0, s[50:51]
	global_load_dword v180, v[230:231], off nt
	v_lshl_add_u64 v[230:231], v[230:231], 0, s[50:51]
	global_load_dword v181, v[230:231], off nt
	s_waitcnt vmcnt(31)
	ds_write_b32 v234, v150
	s_waitcnt vmcnt(30)
	ds_write_b32 v234, v151 offset:264
	s_waitcnt vmcnt(29)
	ds_write_b32 v234, v152 offset:528
	s_waitcnt vmcnt(28)
	ds_write_b32 v234, v153 offset:792
	s_waitcnt vmcnt(27)
	ds_write_b32 v234, v154 offset:1056
	s_waitcnt vmcnt(26)
	ds_write_b32 v234, v155 offset:1320
	s_waitcnt vmcnt(25)
	ds_write_b32 v234, v156 offset:1584
	s_waitcnt vmcnt(24)
	ds_write_b32 v234, v157 offset:1848
	s_waitcnt vmcnt(23)
	ds_write_b32 v234, v158 offset:2112
	s_waitcnt vmcnt(22)
	ds_write_b32 v234, v159 offset:2376
	s_waitcnt vmcnt(21)
	ds_write_b32 v234, v160 offset:2640
	s_waitcnt vmcnt(20)
	ds_write_b32 v234, v161 offset:2904
	s_waitcnt vmcnt(19)
	ds_write_b32 v234, v162 offset:3168
	s_waitcnt vmcnt(18)
	ds_write_b32 v234, v163 offset:3432
	s_waitcnt vmcnt(17)
	ds_write_b32 v234, v164 offset:3696
	s_waitcnt vmcnt(16)
	ds_write_b32 v234, v165 offset:3960
	s_waitcnt vmcnt(15)
	ds_write_b32 v234, v166 offset:4224
	s_waitcnt vmcnt(14)
	ds_write_b32 v234, v167 offset:4488
	s_waitcnt vmcnt(13)
	ds_write_b32 v234, v168 offset:4752
	s_waitcnt vmcnt(12)
	ds_write_b32 v234, v169 offset:5016
	s_waitcnt vmcnt(11)
	ds_write_b32 v234, v170 offset:5280
	s_waitcnt vmcnt(10)
	ds_write_b32 v234, v171 offset:5544
	s_waitcnt vmcnt(9)
	ds_write_b32 v234, v172 offset:5808
	s_waitcnt vmcnt(8)
	ds_write_b32 v234, v173 offset:6072
	s_waitcnt vmcnt(7)
	ds_write_b32 v234, v174 offset:6336
	s_waitcnt vmcnt(6)
	ds_write_b32 v234, v175 offset:6600
	s_waitcnt vmcnt(5)
	ds_write_b32 v234, v176 offset:6864
	s_waitcnt vmcnt(4)
	ds_write_b32 v234, v177 offset:7128
	s_waitcnt vmcnt(3)
	ds_write_b32 v234, v178 offset:7392
	s_waitcnt vmcnt(2)
	ds_write_b32 v234, v179 offset:7656
	s_waitcnt vmcnt(1)
	ds_write_b32 v234, v180 offset:7920
	s_waitcnt vmcnt(0)
	ds_write_b32 v234, v181 offset:8184
	s_mov_b32 s1, 0x40
	v_add_u32_e32 v14, 0x2100, v14
	s_waitcnt lgkmcnt(0)
	ds_read2_b32 v[4:5], v8 offset0:33 offset1:41
	ds_read2_b32 v[18:19], v8 offset1:8
	ds_read2_b32 v[20:21], v8 offset0:66 offset1:74
	ds_read2_b32 v[22:23], v8 offset0:99 offset1:107
	ds_read2_b32 v[24:25], v8 offset0:132 offset1:140
	ds_read2_b32 v[26:27], v8 offset0:165 offset1:173
	ds_read2_b32 v[28:29], v8 offset0:198 offset1:206
	ds_read2_b32 v[30:31], v8 offset0:231 offset1:239
	v_or_b32_e32 v34, s0, v7
	s_ashr_i32 s5, s4, 31
	v_ashrrev_i32_e32 v35, 31, v34
	v_lshl_add_u64 v[32:33], s[4:5], 1, v[2:3]
	v_lshlrev_b64 v[34:35], 11, v[34:35]
	s_waitcnt lgkmcnt(6)
	v_cvt_pk_bf16_f32 v14, v18, v4
	s_waitcnt lgkmcnt(4)
	v_cvt_pk_bf16_f32 v15, v20, v22
	s_waitcnt lgkmcnt(2)
	v_cvt_pk_bf16_f32 v16, v24, v26
	s_waitcnt lgkmcnt(0)
	v_cvt_pk_bf16_f32 v17, v28, v30
	v_lshl_add_u64 v[34:35], v[32:33], 0, v[34:35]
	v_or_b32_e32 v4, s0, v9
	global_store_dwordx4 v[34:35], v[14:17], off
	s_add_i32 s6, s6, s96
	s_cmpk_lt_i32 s6, 0x200
	v_cvt_pk_bf16_f32 v14, v19, v5
	v_ashrrev_i32_e32 v5, 31, v4
	v_cvt_pk_bf16_f32 v15, v21, v23
	v_cvt_pk_bf16_f32 v16, v25, v27
	v_cvt_pk_bf16_f32 v17, v29, v31
	v_lshlrev_b64 v[4:5], 11, v[4:5]
	ds_read2_b32 v[18:19], v8 offset0:49 offset1:57
	ds_read2_b32 v[20:21], v8 offset0:16 offset1:24
	ds_read2_b32 v[22:23], v8 offset0:82 offset1:90
	ds_read2_b32 v[24:25], v8 offset0:115 offset1:123
	ds_read2_b32 v[26:27], v8 offset0:148 offset1:156
	ds_read2_b32 v[28:29], v8 offset0:181 offset1:189
	ds_read2_b32 v[30:31], v8 offset0:214 offset1:222
	ds_read2_b32 v[34:35], v8 offset0:247 offset1:255
	v_lshl_add_u64 v[4:5], v[32:33], 0, v[4:5]
	global_store_dwordx4 v[4:5], v[14:17], off
	v_or_b32_e32 v4, s0, v10
	v_ashrrev_i32_e32 v5, 31, v4
	v_lshlrev_b64 v[4:5], 11, v[4:5]
	s_waitcnt lgkmcnt(6)
	v_cvt_pk_bf16_f32 v14, v20, v18
	s_waitcnt lgkmcnt(4)
	v_cvt_pk_bf16_f32 v15, v22, v24
	s_waitcnt lgkmcnt(2)
	v_cvt_pk_bf16_f32 v16, v26, v28
	s_waitcnt lgkmcnt(0)
	v_cvt_pk_bf16_f32 v17, v30, v34
	v_lshl_add_u64 v[4:5], v[32:33], 0, v[4:5]
	global_store_dwordx4 v[4:5], v[14:17], off
	v_or_b32_e32 v4, s0, v11
	v_ashrrev_i32_e32 v5, 31, v4
	v_lshlrev_b64 v[4:5], 11, v[4:5]
	v_cvt_pk_bf16_f32 v14, v21, v19
	v_cvt_pk_bf16_f32 v15, v23, v25
	v_cvt_pk_bf16_f32 v16, v27, v29
	v_cvt_pk_bf16_f32 v17, v31, v35
	v_lshl_add_u64 v[4:5], v[32:33], 0, v[4:5]
	global_store_dwordx4 v[4:5], v[14:17], off
	s_waitcnt lgkmcnt(0)
	s_cbranch_scc1 .LBB0_516

.LBB0_805:
	s_cmpk_gt_i32 s33, 0xaff
	s_mov_b64 s[10:11], -1
	s_cbranch_scc0 .LBB0_809
	s_lshl_b32 s6, s16, 2
	s_and_b32 s12, s18, 0x1ffc0
	s_and_b32 s6, s6, 0xf80
	v_or_b32_e32 v10, s12, v50
	v_lshl_or_b32 v12, v10, 12, s6
	v_or_b32_e32 v10, s12, v51
	v_lshl_or_b32 v14, v10, 12, s6
	v_or_b32_e32 v10, s12, v52
	s_load_dwordx2 s[10:11], s[0:1], 0x20
	v_lshl_or_b32 v16, v10, 12, s6
	v_or_b32_e32 v10, s12, v53
	v_lshl_or_b32 v18, v10, 12, s6
	v_or_b32_e32 v10, s12, v54
	v_lshl_or_b32 v20, v10, 12, s6
	v_or_b32_e32 v10, s12, v55
	v_or_b32_e32 v0, s12, v49
	v_lshl_or_b32 v22, v10, 12, s6
	v_or_b32_e32 v10, s12, v42
	v_lshl_or_b32 v0, v0, 12, s6
	v_mov_b32_e32 v13, v1
	v_mov_b32_e32 v15, v1
	v_mov_b32_e32 v17, v1
	v_mov_b32_e32 v19, v1
	v_mov_b32_e32 v21, v1
	v_mov_b32_e32 v23, v1
	v_lshl_or_b32 v24, v10, 12, s6
	v_mov_b32_e32 v25, v1
	s_waitcnt lgkmcnt(0)
	v_lshl_add_u64 v[26:27], s[10:11], 0, v[8:9]
	v_lshl_add_u64 v[10:11], v[26:27], 0, v[0:1]
	v_lshl_add_u64 v[12:13], v[26:27], 0, v[12:13]
	v_lshl_add_u64 v[14:15], v[26:27], 0, v[14:15]
	v_lshl_add_u64 v[16:17], v[26:27], 0, v[16:17]
	v_lshl_add_u64 v[18:19], v[26:27], 0, v[18:19]
	v_lshl_add_u64 v[20:21], v[26:27], 0, v[20:21]
	v_lshl_add_u64 v[22:23], v[26:27], 0, v[22:23]
	v_lshl_add_u64 v[24:25], v[26:27], 0, v[24:25]
	s_mov_b64 s[10:11], 0
	v_mov_b32_e32 v0, v48
	v_mov_b32_e32 v230, v24
	v_mov_b32_e32 v231, v25
	v_mov_b32_e32 v234, v0
	s_mov_b32 s56, 0x2000
	s_mov_b32 s57, 0
	global_load_dword v150, v[230:231], off nt
	v_lshl_add_u64 v[230:231], v[230:231], 0, s[56:57]
	global_load_dword v151, v[230:231], off nt
	v_lshl_add_u64 v[230:231], v[230:231], 0, s[56:57]
	global_load_dword v152, v[230:231], off nt
	v_lshl_add_u64 v[230:231], v[230:231], 0, s[56:57]
	global_load_dword v153, v[230:231], off nt
	v_lshl_add_u64 v[230:231], v[230:231], 0, s[56:57]
	global_load_dword v154, v[230:231], off nt
	v_lshl_add_u64 v[230:231], v[230:231], 0, s[56:57]
	global_load_dword v155, v[230:231], off nt
	v_lshl_add_u64 v[230:231], v[230:231], 0, s[56:57]
	global_load_dword v156, v[230:231], off nt
	v_lshl_add_u64 v[230:231], v[230:231], 0, s[56:57]
	global_load_dword v157, v[230:231], off nt
	v_lshl_add_u64 v[230:231], v[230:231], 0, s[56:57]
	global_load_dword v158, v[230:231], off nt
	v_lshl_add_u64 v[230:231], v[230:231], 0, s[56:57]
	global_load_dword v159, v[230:231], off nt
	v_lshl_add_u64 v[230:231], v[230:231], 0, s[56:57]
	global_load_dword v160, v[230:231], off nt
	v_lshl_add_u64 v[230:231], v[230:231], 0, s[56:57]
	global_load_dword v161, v[230:231], off nt
	v_lshl_add_u64 v[230:231], v[230:231], 0, s[56:57]
	global_load_dword v162, v[230:231], off nt
	v_lshl_add_u64 v[230:231], v[230:231], 0, s[56:57]
	global_load_dword v163, v[230:231], off nt
	v_lshl_add_u64 v[230:231], v[230:231], 0, s[56:57]
	global_load_dword v164, v[230:231], off nt
	v_lshl_add_u64 v[230:231], v[230:231], 0, s[56:57]
	global_load_dword v165, v[230:231], off nt
	v_lshl_add_u64 v[230:231], v[230:231], 0, s[56:57]
	global_load_dword v166, v[230:231], off nt
	v_lshl_add_u64 v[230:231], v[230:231], 0, s[56:57]
	global_load_dword v167, v[230:231], off nt
	v_lshl_add_u64 v[230:231], v[230:231], 0, s[56:57]
	global_load_dword v168, v[230:231], off nt
	v_lshl_add_u64 v[230:231], v[230:231], 0, s[56:57]
	global_load_dword v169, v[230:231], off nt
	v_lshl_add_u64 v[230:231], v[230:231], 0, s[56:57]
	global_load_dword v170, v[230:231], off nt
	v_lshl_add_u64 v[230:231], v[230:231], 0, s[56:57]
	global_load_dword v171, v[230:231], off nt
	v_lshl_add_u64 v[230:231], v[230:231], 0, s[56:57]
	global_load_dword v172, v[230:231], off nt
	v_lshl_add_u64 v[230:231], v[230:231], 0, s[56:57]
	global_load_dword v173, v[230:231], off nt
	v_lshl_add_u64 v[230:231], v[230:231], 0, s[56:57]
	global_load_dword v174, v[230:231], off nt
	v_lshl_add_u64 v[230:231], v[230:231], 0, s[56:57]
	global_load_dword v175, v[230:231], off nt
	v_lshl_add_u64 v[230:231], v[230:231], 0, s[56:57]
	global_load_dword v176, v[230:231], off nt
	v_lshl_add_u64 v[230:231], v[230:231], 0, s[56:57]
	global_load_dword v177, v[230:231], off nt
	v_lshl_add_u64 v[230:231], v[230:231], 0, s[56:57]
	global_load_dword v178, v[230:231], off nt
	v_lshl_add_u64 v[230:231], v[230:231], 0, s[56:57]
	global_load_dword v179, v[230:231], off nt
	v_lshl_add_u64 v[230:231], v[230:231], 0, s[56:57]
	global_load_dword v180, v[230:231], off nt
	v_lshl_add_u64 v[230:231], v[230:231], 0, s[56:57]
	global_load_dword v181, v[230:231], off nt
	s_waitcnt vmcnt(31)
	ds_write_b32 v234, v150
	s_waitcnt vmcnt(30)
	ds_write_b32 v234, v151 offset:264
	s_waitcnt vmcnt(29)
	ds_write_b32 v234, v152 offset:528
	s_waitcnt vmcnt(28)
	ds_write_b32 v234, v153 offset:792
	s_waitcnt vmcnt(27)
	ds_write_b32 v234, v154 offset:1056
	s_waitcnt vmcnt(26)
	ds_write_b32 v234, v155 offset:1320
	s_waitcnt vmcnt(25)
	ds_write_b32 v234, v156 offset:1584
	s_waitcnt vmcnt(24)
	ds_write_b32 v234, v157 offset:1848
	s_waitcnt vmcnt(23)
	ds_write_b32 v234, v158 offset:2112
	s_waitcnt vmcnt(22)
	ds_write_b32 v234, v159 offset:2376
	s_waitcnt vmcnt(21)
	ds_write_b32 v234, v160 offset:2640
	s_waitcnt vmcnt(20)
	ds_write_b32 v234, v161 offset:2904
	s_waitcnt vmcnt(19)
	ds_write_b32 v234, v162 offset:3168
	s_waitcnt vmcnt(18)
	ds_write_b32 v234, v163 offset:3432
	s_waitcnt vmcnt(17)
	ds_write_b32 v234, v164 offset:3696
	s_waitcnt vmcnt(16)
	ds_write_b32 v234, v165 offset:3960
	s_waitcnt vmcnt(15)
	ds_write_b32 v234, v166 offset:4224
	s_waitcnt vmcnt(14)
	ds_write_b32 v234, v167 offset:4488
	s_waitcnt vmcnt(13)
	ds_write_b32 v234, v168 offset:4752
	s_waitcnt vmcnt(12)
	ds_write_b32 v234, v169 offset:5016
	s_waitcnt vmcnt(11)
	ds_write_b32 v234, v170 offset:5280
	s_waitcnt vmcnt(10)
	ds_write_b32 v234, v171 offset:5544
	s_waitcnt vmcnt(9)
	ds_write_b32 v234, v172 offset:5808
	s_waitcnt vmcnt(8)
	ds_write_b32 v234, v173 offset:6072
	s_waitcnt vmcnt(7)
	ds_write_b32 v234, v174 offset:6336
	s_waitcnt vmcnt(6)
	ds_write_b32 v234, v175 offset:6600
	s_waitcnt vmcnt(5)
	ds_write_b32 v234, v176 offset:6864
	s_waitcnt vmcnt(4)
	ds_write_b32 v234, v177 offset:7128
	s_waitcnt vmcnt(3)
	ds_write_b32 v234, v178 offset:7392
	s_waitcnt vmcnt(2)
	ds_write_b32 v234, v179 offset:7656
	s_waitcnt vmcnt(1)
	ds_write_b32 v234, v180 offset:7920
	s_waitcnt vmcnt(0)
	ds_write_b32 v234, v181 offset:8184
	s_mov_b32 s10, 0x40000
	v_add_u32_e32 v0, 0x2100, v0
	s_waitcnt lgkmcnt(0)
	s_lshl_b32 s6, s33, 1
	s_lshl_b32 s10, s33, 5
	s_add_i32 s6, s6, 0x1ea00
	s_and_b32 s10, s10, 0x3e0
	ds_read2_b32 v[14:15], v44 offset0:33 offset1:41
	ds_read2_b32 v[16:17], v44 offset1:8
	ds_read2_b32 v[18:19], v44 offset0:66 offset1:74
	ds_read2_b32 v[20:21], v44 offset0:99 offset1:107
	ds_read2_b32 v[22:23], v44 offset0:132 offset1:140
	ds_read2_b32 v[24:25], v44 offset0:165 offset1:173
	ds_read2_b32 v[26:27], v44 offset0:198 offset1:206
	ds_read2_b32 v[28:29], v44 offset0:231 offset1:239
	s_and_b32 s6, s6, 0x1ffc0
	v_or_b32_e32 v0, s10, v43
	s_lshl_b32 s6, s6, 1
	v_mul_u32_u24_e32 v0, 0xb00, v0
	v_lshl_add_u64 v[30:31], v[2:3], 0, s[6:7]
	v_lshlrev_b32_e32 v0, 1, v0
	v_lshl_add_u64 v[32:33], v[30:31], 0, v[0:1]
	v_or_b32_e32 v0, s10, v45
	s_waitcnt lgkmcnt(6)
	v_cvt_pk_bf16_f32 v10, v16, v14
	s_waitcnt lgkmcnt(4)
	v_cvt_pk_bf16_f32 v11, v18, v20
	s_waitcnt lgkmcnt(2)
	v_cvt_pk_bf16_f32 v12, v22, v24
	s_waitcnt lgkmcnt(0)
	v_cvt_pk_bf16_f32 v13, v26, v28
	v_mul_u32_u24_e32 v0, 0xb00, v0
	global_store_dwordx4 v[32:33], v[10:13], off
	v_lshlrev_b32_e32 v0, 1, v0
	s_nop 0
	v_cvt_pk_bf16_f32 v10, v17, v15
	v_cvt_pk_bf16_f32 v11, v19, v21
	v_cvt_pk_bf16_f32 v12, v23, v25
	v_cvt_pk_bf16_f32 v13, v27, v29
	v_lshl_add_u64 v[14:15], v[30:31], 0, v[0:1]
	ds_read2_b32 v[16:17], v44 offset0:16 offset1:24
	ds_read2_b32 v[18:19], v44 offset0:49 offset1:57
	ds_read2_b32 v[20:21], v44 offset0:82 offset1:90
	ds_read2_b32 v[22:23], v44 offset0:115 offset1:123
	ds_read2_b32 v[24:25], v44 offset0:148 offset1:156
	ds_read2_b32 v[26:27], v44 offset0:181 offset1:189
	ds_read2_b32 v[28:29], v44 offset0:214 offset1:222
	ds_read2_b32 v[32:33], v44 offset0:247 offset1:255
	v_or_b32_e32 v0, s10, v46
	v_mul_u32_u24_e32 v0, 0xb00, v0
	v_lshlrev_b32_e32 v0, 1, v0
	global_store_dwordx4 v[14:15], v[10:13], off
	v_lshl_add_u64 v[14:15], v[30:31], 0, v[0:1]
	v_or_b32_e32 v0, s10, v47
	v_mul_u32_u24_e32 v0, 0xb00, v0
	s_waitcnt lgkmcnt(6)
	v_cvt_pk_bf16_f32 v10, v16, v18
	s_waitcnt lgkmcnt(4)
	v_cvt_pk_bf16_f32 v11, v20, v22
	s_waitcnt lgkmcnt(2)
	v_cvt_pk_bf16_f32 v12, v24, v26
	s_waitcnt lgkmcnt(0)
	v_cvt_pk_bf16_f32 v13, v28, v32
	v_lshlrev_b32_e32 v0, 1, v0
	global_store_dwordx4 v[14:15], v[10:13], off
	v_lshl_add_u64 v[14:15], v[30:31], 0, v[0:1]
	s_mov_b64 s[10:11], 0
	v_cvt_pk_bf16_f32 v10, v17, v19
	v_cvt_pk_bf16_f32 v11, v21, v23
	v_cvt_pk_bf16_f32 v12, v25, v27
	v_cvt_pk_bf16_f32 v13, v29, v33
	global_store_dwordx4 v[14:15], v[10:13], off
	s_waitcnt lgkmcnt(0)
.LBB0_809:
	s_and_b64 vcc, exec, s[10:11]
	s_cbranch_vccz .LBB0_804
	s_mul_hi_i32 s6, s33, 0x2e8ba2e9
	s_lshr_b32 s10, s6, 31
	s_ashr_i32 s6, s6, 5
	s_add_i32 s10, s6, s10
	s_load_dwordx2 s[14:15], s[0:1], 0x18
	s_mul_i32 s6, s10, 0xb0
	s_sub_i32 s6, s33, s6
	s_lshl_b32 s12, s6, 5
	s_ashr_i32 s13, s12, 31
	s_lshl_b32 s10, s10, 6
	s_lshl_b64 s[22:23], s[12:13], 2
	s_waitcnt lgkmcnt(0)
	s_add_u32 s11, s14, s22
	s_addc_u32 s13, s15, s23
	s_add_u32 s14, s11, 0x1600000
	v_or_b32_e32 v12, s10, v49
	s_addc_u32 s15, s13, 0
	v_or_b32_e32 v16, s10, v50
	v_or_b32_e32 v20, s10, v51
	v_or_b32_e32 v24, s10, v52
	v_or_b32_e32 v28, s10, v53
	v_or_b32_e32 v32, s10, v54
	v_or_b32_e32 v36, s10, v55
	v_ashrrev_i32_e32 v13, 31, v12
	v_mov_b64_e32 v[40:41], s[14:15]
	v_ashrrev_i32_e32 v17, 31, v16
	v_ashrrev_i32_e32 v21, 31, v20
	v_ashrrev_i32_e32 v25, 31, v24
	v_ashrrev_i32_e32 v29, 31, v28
	v_ashrrev_i32_e32 v33, 31, v32
	v_ashrrev_i32_e32 v37, 31, v36
	v_or_b32_e32 v56, s10, v42
	v_lshl_add_u64 v[10:11], v[12:13], 2, s[4:5]
	v_mad_i64_i32 v[12:13], s[14:15], v12, s20, v[40:41]
	v_lshl_add_u64 v[14:15], v[16:17], 2, s[4:5]
	v_mad_i64_i32 v[16:17], s[14:15], v16, s20, v[40:41]
	v_lshl_add_u64 v[18:19], v[20:21], 2, s[4:5]
	v_mad_i64_i32 v[20:21], s[14:15], v20, s20, v[40:41]
	v_lshl_add_u64 v[22:23], v[24:25], 2, s[4:5]
	v_mad_i64_i32 v[24:25], s[14:15], v24, s20, v[40:41]
	v_lshl_add_u64 v[26:27], v[28:29], 2, s[4:5]
	v_mad_i64_i32 v[28:29], s[14:15], v28, s20, v[40:41]
	v_lshl_add_u64 v[30:31], v[32:33], 2, s[4:5]
	v_mad_i64_i32 v[32:33], s[14:15], v32, s20, v[40:41]
	v_lshl_add_u64 v[34:35], v[36:37], 2, s[4:5]
	v_mad_i64_i32 v[36:37], s[14:15], v36, s20, v[40:41]
	v_ashrrev_i32_e32 v57, 31, v56
	v_mad_i64_i32 v[40:41], s[14:15], v56, s20, v[40:41]
	v_lshl_add_u64 v[38:39], v[56:57], 2, s[4:5]
	s_mov_b64 s[14:15], 0
	v_mov_b32_e32 v0, v48
	v_lshl_add_u64 v[230:231], v[40:41], 0, v[6:7]
	v_mov_b32_e32 v232, v38
	v_mov_b32_e32 v233, v39
	v_mov_b32_e32 v234, v0
	s_mov_b32 s56, 0xb000
	s_mov_b32 s57, 0
	global_load_dword v150, v[230:231], off nt
	v_lshl_add_u64 v[230:231], v[230:231], 0, s[56:57]
	global_load_dword v151, v[230:231], off nt
	v_lshl_add_u64 v[230:231], v[230:231], 0, s[56:57]
	global_load_dword v152, v[230:231], off nt
	v_lshl_add_u64 v[230:231], v[230:231], 0, s[56:57]
	global_load_dword v153, v[230:231], off nt
	v_lshl_add_u64 v[230:231], v[230:231], 0, s[56:57]
	global_load_dword v154, v[230:231], off nt
	v_lshl_add_u64 v[230:231], v[230:231], 0, s[56:57]
	global_load_dword v155, v[230:231], off nt
	v_lshl_add_u64 v[230:231], v[230:231], 0, s[56:57]
	global_load_dword v156, v[230:231], off nt
	v_lshl_add_u64 v[230:231], v[230:231], 0, s[56:57]
	global_load_dword v157, v[230:231], off nt
	v_lshl_add_u64 v[230:231], v[230:231], 0, s[56:57]
	global_load_dword v158, v[230:231], off nt
	v_lshl_add_u64 v[230:231], v[230:231], 0, s[56:57]
	global_load_dword v159, v[230:231], off nt
	v_lshl_add_u64 v[230:231], v[230:231], 0, s[56:57]
	global_load_dword v160, v[230:231], off nt
	v_lshl_add_u64 v[230:231], v[230:231], 0, s[56:57]
	global_load_dword v161, v[230:231], off nt
	v_lshl_add_u64 v[230:231], v[230:231], 0, s[56:57]
	global_load_dword v162, v[230:231], off nt
	v_lshl_add_u64 v[230:231], v[230:231], 0, s[56:57]
	global_load_dword v163, v[230:231], off nt
	v_lshl_add_u64 v[230:231], v[230:231], 0, s[56:57]
	global_load_dword v164, v[230:231], off nt
	v_lshl_add_u64 v[230:231], v[230:231], 0, s[56:57]
	global_load_dword v165, v[230:231], off nt
	v_lshl_add_u64 v[230:231], v[230:231], 0, s[56:57]
	global_load_dword v166, v[230:231], off nt
	v_lshl_add_u64 v[230:231], v[230:231], 0, s[56:57]
	global_load_dword v167, v[230:231], off nt
	v_lshl_add_u64 v[230:231], v[230:231], 0, s[56:57]
	global_load_dword v168, v[230:231], off nt
	v_lshl_add_u64 v[230:231], v[230:231], 0, s[56:57]
	global_load_dword v169, v[230:231], off nt
	v_lshl_add_u64 v[230:231], v[230:231], 0, s[56:57]
	global_load_dword v170, v[230:231], off nt
	v_lshl_add_u64 v[230:231], v[230:231], 0, s[56:57]
	global_load_dword v171, v[230:231], off nt
	v_lshl_add_u64 v[230:231], v[230:231], 0, s[56:57]
	global_load_dword v172, v[230:231], off nt
	v_lshl_add_u64 v[230:231], v[230:231], 0, s[56:57]
	global_load_dword v173, v[230:231], off nt
	v_lshl_add_u64 v[230:231], v[230:231], 0, s[56:57]
	global_load_dword v174, v[230:231], off nt
	v_lshl_add_u64 v[230:231], v[230:231], 0, s[56:57]
	global_load_dword v175, v[230:231], off nt
	v_lshl_add_u64 v[230:231], v[230:231], 0, s[56:57]
	global_load_dword v176, v[230:231], off nt
	v_lshl_add_u64 v[230:231], v[230:231], 0, s[56:57]
	global_load_dword v177, v[230:231], off nt
	v_lshl_add_u64 v[230:231], v[230:231], 0, s[56:57]
	global_load_dword v178, v[230:231], off nt
	v_lshl_add_u64 v[230:231], v[230:231], 0, s[56:57]
	global_load_dword v179, v[230:231], off nt
	v_lshl_add_u64 v[230:231], v[230:231], 0, s[56:57]
	global_load_dword v180, v[230:231], off nt
	v_lshl_add_u64 v[230:231], v[230:231], 0, s[56:57]
	global_load_dword v181, v[230:231], off nt
	global_load_dword v182, v[232:233], off
	global_load_dword v183, v[232:233], off offset:8
	global_load_dword v184, v[232:233], off offset:16
	global_load_dword v185, v[232:233], off offset:24
	global_load_dword v186, v[232:233], off offset:32
	global_load_dword v187, v[232:233], off offset:40
	global_load_dword v188, v[232:233], off offset:48
	global_load_dword v189, v[232:233], off offset:56
	global_load_dword v190, v[232:233], off offset:64
	global_load_dword v191, v[232:233], off offset:72
	global_load_dword v192, v[232:233], off offset:80
	global_load_dword v193, v[232:233], off offset:88
	global_load_dword v194, v[232:233], off offset:96
	global_load_dword v195, v[232:233], off offset:104
	global_load_dword v196, v[232:233], off offset:112
	global_load_dword v197, v[232:233], off offset:120
	s_waitcnt vmcnt(15)
	v_mul_f32_e32 v150, v150, v182
	ds_write_b32 v234, v150
	s_waitcnt vmcnt(14)
	v_mul_f32_e32 v151, v151, v183
	ds_write_b32 v234, v151 offset:264
	s_waitcnt vmcnt(13)
	v_mul_f32_e32 v152, v152, v184
	ds_write_b32 v234, v152 offset:528
	s_waitcnt vmcnt(12)
	v_mul_f32_e32 v153, v153, v185
	ds_write_b32 v234, v153 offset:792
	s_waitcnt vmcnt(11)
	v_mul_f32_e32 v154, v154, v186
	ds_write_b32 v234, v154 offset:1056
	s_waitcnt vmcnt(10)
	v_mul_f32_e32 v155, v155, v187
	ds_write_b32 v234, v155 offset:1320
	s_waitcnt vmcnt(9)
	v_mul_f32_e32 v156, v156, v188
	ds_write_b32 v234, v156 offset:1584
	s_waitcnt vmcnt(8)
	v_mul_f32_e32 v157, v157, v189
	ds_write_b32 v234, v157 offset:1848
	s_waitcnt vmcnt(7)
	v_mul_f32_e32 v158, v158, v190
	ds_write_b32 v234, v158 offset:2112
	s_waitcnt vmcnt(6)
	v_mul_f32_e32 v159, v159, v191
	ds_write_b32 v234, v159 offset:2376
	s_waitcnt vmcnt(5)
	v_mul_f32_e32 v160, v160, v192
	ds_write_b32 v234, v160 offset:2640
	s_waitcnt vmcnt(4)
	v_mul_f32_e32 v161, v161, v193
	ds_write_b32 v234, v161 offset:2904
	s_waitcnt vmcnt(3)
	v_mul_f32_e32 v162, v162, v194
	ds_write_b32 v234, v162 offset:3168
	s_waitcnt vmcnt(2)
	v_mul_f32_e32 v163, v163, v195
	ds_write_b32 v234, v163 offset:3432
	s_waitcnt vmcnt(1)
	v_mul_f32_e32 v164, v164, v196
	ds_write_b32 v234, v164 offset:3696
	s_waitcnt vmcnt(0)
	v_mul_f32_e32 v165, v165, v197
	ds_write_b32 v234, v165 offset:3960
	global_load_dword v182, v[232:233], off offset:128
	global_load_dword v183, v[232:233], off offset:136
	global_load_dword v184, v[232:233], off offset:144
	global_load_dword v185, v[232:233], off offset:152
	global_load_dword v186, v[232:233], off offset:160
	global_load_dword v187, v[232:233], off offset:168
	global_load_dword v188, v[232:233], off offset:176
	global_load_dword v189, v[232:233], off offset:184
	global_load_dword v190, v[232:233], off offset:192
	global_load_dword v191, v[232:233], off offset:200
	global_load_dword v192, v[232:233], off offset:208
	global_load_dword v193, v[232:233], off offset:216
	global_load_dword v194, v[232:233], off offset:224
	global_load_dword v195, v[232:233], off offset:232
	global_load_dword v196, v[232:233], off offset:240
	global_load_dword v197, v[232:233], off offset:248
	s_waitcnt vmcnt(15)
	v_mul_f32_e32 v166, v166, v182
	ds_write_b32 v234, v166 offset:4224
	s_waitcnt vmcnt(14)
	v_mul_f32_e32 v167, v167, v183
	ds_write_b32 v234, v167 offset:4488
	s_waitcnt vmcnt(13)
	v_mul_f32_e32 v168, v168, v184
	ds_write_b32 v234, v168 offset:4752
	s_waitcnt vmcnt(12)
	v_mul_f32_e32 v169, v169, v185
	ds_write_b32 v234, v169 offset:5016
	s_waitcnt vmcnt(11)
	v_mul_f32_e32 v170, v170, v186
	ds_write_b32 v234, v170 offset:5280
	s_waitcnt vmcnt(10)
	v_mul_f32_e32 v171, v171, v187
	ds_write_b32 v234, v171 offset:5544
	s_waitcnt vmcnt(9)
	v_mul_f32_e32 v172, v172, v188
	ds_write_b32 v234, v172 offset:5808
	s_waitcnt vmcnt(8)
	v_mul_f32_e32 v173, v173, v189
	ds_write_b32 v234, v173 offset:6072
	s_waitcnt vmcnt(7)
	v_mul_f32_e32 v174, v174, v190
	ds_write_b32 v234, v174 offset:6336
	s_waitcnt vmcnt(6)
	v_mul_f32_e32 v175, v175, v191
	ds_write_b32 v234, v175 offset:6600
	s_waitcnt vmcnt(5)
	v_mul_f32_e32 v176, v176, v192
	ds_write_b32 v234, v176 offset:6864
	s_waitcnt vmcnt(4)
	v_mul_f32_e32 v177, v177, v193
	ds_write_b32 v234, v177 offset:7128
	s_waitcnt vmcnt(3)
	v_mul_f32_e32 v178, v178, v194
	ds_write_b32 v234, v178 offset:7392
	s_waitcnt vmcnt(2)
	v_mul_f32_e32 v179, v179, v195
	ds_write_b32 v234, v179 offset:7656
	s_waitcnt vmcnt(1)
	v_mul_f32_e32 v180, v180, v196
	ds_write_b32 v234, v180 offset:7920
	s_waitcnt vmcnt(0)
	v_mul_f32_e32 v181, v181, v197
	ds_write_b32 v234, v181 offset:8184
	s_mov_b32 s14, 0x100
	v_add_u32_e32 v0, 0x2100, v0
	s_waitcnt lgkmcnt(0)
	s_lshl_b32 s11, s6, 6
	s_cmpk_gt_i32 s6, 0x57
	s_mov_b64 s[14:15], -1
	s_cbranch_scc0 .LBB0_814
	s_add_i32 s6, s11, 0x7fffea00
	s_and_b32 s6, s6, 0x7fffff00
	s_and_b32 s13, s12, 0x60
	s_or_b32 s6, s13, s6
	s_bitset1_b32 s6, 7
	s_mov_b64 s[14:15], 0

.LBB0_1034:
	s_cmpk_gt_i32 s33, 0x1ff
	s_mov_b64 s[10:11], -1
	s_cbranch_scc0 .LBB0_1038
	s_load_dwordx2 s[10:11], s[0:1], 0x28
	s_lshl_b32 s8, s14, 2
	s_and_b32 s12, s16, 0x1c0
	s_and_b32 s8, s8, 0xf80
	v_or_b32_e32 v8, s12, v31
	v_or_b32_e32 v10, s12, v32
	v_or_b32_e32 v12, s12, v33
	v_or_b32_e32 v14, s12, v34
	v_or_b32_e32 v16, s12, v35
	v_or_b32_e32 v18, s12, v36
	v_or_b32_e32 v20, s12, v37
	v_or_b32_e32 v22, s12, v24
	v_lshl_or_b32 v8, v8, 12, s8
	v_mov_b32_e32 v9, v1
	v_lshl_or_b32 v10, v10, 12, s8
	v_mov_b32_e32 v11, v1
	v_lshl_or_b32 v12, v12, 12, s8
	v_mov_b32_e32 v13, v1
	v_lshl_or_b32 v14, v14, 12, s8
	v_mov_b32_e32 v15, v1
	v_lshl_or_b32 v16, v16, 12, s8
	v_mov_b32_e32 v17, v1
	v_lshl_or_b32 v18, v18, 12, s8
	v_mov_b32_e32 v19, v1
	v_lshl_or_b32 v20, v20, 12, s8
	v_mov_b32_e32 v21, v1
	v_lshl_or_b32 v22, v22, 12, s8
	v_mov_b32_e32 v23, v1
	s_waitcnt lgkmcnt(0)
	v_lshl_add_u64 v[38:39], s[10:11], 0, v[6:7]
	v_lshl_add_u64 v[8:9], v[38:39], 0, v[8:9]
	v_lshl_add_u64 v[10:11], v[38:39], 0, v[10:11]
	v_lshl_add_u64 v[12:13], v[38:39], 0, v[12:13]
	v_lshl_add_u64 v[14:15], v[38:39], 0, v[14:15]
	v_lshl_add_u64 v[16:17], v[38:39], 0, v[16:17]
	v_lshl_add_u64 v[18:19], v[38:39], 0, v[18:19]
	v_lshl_add_u64 v[20:21], v[38:39], 0, v[20:21]
	v_lshl_add_u64 v[22:23], v[38:39], 0, v[22:23]
	s_mov_b64 s[10:11], 0
	v_mov_b32_e32 v38, v30
	v_mov_b32_e32 v230, v22
	v_mov_b32_e32 v231, v23
	v_mov_b32_e32 v234, v38
	s_mov_b32 s70, 0x2000
	s_mov_b32 s71, 0
	global_load_dword v150, v[230:231], off nt
	v_lshl_add_u64 v[230:231], v[230:231], 0, s[70:71]
	global_load_dword v151, v[230:231], off nt
	v_lshl_add_u64 v[230:231], v[230:231], 0, s[70:71]
	global_load_dword v152, v[230:231], off nt
	v_lshl_add_u64 v[230:231], v[230:231], 0, s[70:71]
	global_load_dword v153, v[230:231], off nt
	v_lshl_add_u64 v[230:231], v[230:231], 0, s[70:71]
	global_load_dword v154, v[230:231], off nt
	v_lshl_add_u64 v[230:231], v[230:231], 0, s[70:71]
	global_load_dword v155, v[230:231], off nt
	v_lshl_add_u64 v[230:231], v[230:231], 0, s[70:71]
	global_load_dword v156, v[230:231], off nt
	v_lshl_add_u64 v[230:231], v[230:231], 0, s[70:71]
	global_load_dword v157, v[230:231], off nt
	v_lshl_add_u64 v[230:231], v[230:231], 0, s[70:71]
	global_load_dword v158, v[230:231], off nt
	v_lshl_add_u64 v[230:231], v[230:231], 0, s[70:71]
	global_load_dword v159, v[230:231], off nt
	v_lshl_add_u64 v[230:231], v[230:231], 0, s[70:71]
	global_load_dword v160, v[230:231], off nt
	v_lshl_add_u64 v[230:231], v[230:231], 0, s[70:71]
	global_load_dword v161, v[230:231], off nt
	v_lshl_add_u64 v[230:231], v[230:231], 0, s[70:71]
	global_load_dword v162, v[230:231], off nt
	v_lshl_add_u64 v[230:231], v[230:231], 0, s[70:71]
	global_load_dword v163, v[230:231], off nt
	v_lshl_add_u64 v[230:231], v[230:231], 0, s[70:71]
	global_load_dword v164, v[230:231], off nt
	v_lshl_add_u64 v[230:231], v[230:231], 0, s[70:71]
	global_load_dword v165, v[230:231], off nt
	v_lshl_add_u64 v[230:231], v[230:231], 0, s[70:71]
	global_load_dword v166, v[230:231], off nt
	v_lshl_add_u64 v[230:231], v[230:231], 0, s[70:71]
	global_load_dword v167, v[230:231], off nt
	v_lshl_add_u64 v[230:231], v[230:231], 0, s[70:71]
	global_load_dword v168, v[230:231], off nt
	v_lshl_add_u64 v[230:231], v[230:231], 0, s[70:71]
	global_load_dword v169, v[230:231], off nt
	v_lshl_add_u64 v[230:231], v[230:231], 0, s[70:71]
	global_load_dword v170, v[230:231], off nt
	v_lshl_add_u64 v[230:231], v[230:231], 0, s[70:71]
	global_load_dword v171, v[230:231], off nt
	v_lshl_add_u64 v[230:231], v[230:231], 0, s[70:71]
	global_load_dword v172, v[230:231], off nt
	v_lshl_add_u64 v[230:231], v[230:231], 0, s[70:71]
	global_load_dword v173, v[230:231], off nt
	v_lshl_add_u64 v[230:231], v[230:231], 0, s[70:71]
	global_load_dword v174, v[230:231], off nt
	v_lshl_add_u64 v[230:231], v[230:231], 0, s[70:71]
	global_load_dword v175, v[230:231], off nt
	v_lshl_add_u64 v[230:231], v[230:231], 0, s[70:71]
	global_load_dword v176, v[230:231], off nt
	v_lshl_add_u64 v[230:231], v[230:231], 0, s[70:71]
	global_load_dword v177, v[230:231], off nt
	v_lshl_add_u64 v[230:231], v[230:231], 0, s[70:71]
	global_load_dword v178, v[230:231], off nt
	v_lshl_add_u64 v[230:231], v[230:231], 0, s[70:71]
	global_load_dword v179, v[230:231], off nt
	v_lshl_add_u64 v[230:231], v[230:231], 0, s[70:71]
	global_load_dword v180, v[230:231], off nt
	v_lshl_add_u64 v[230:231], v[230:231], 0, s[70:71]
	global_load_dword v181, v[230:231], off nt
	s_waitcnt vmcnt(31)
	ds_write_b32 v234, v150
	s_waitcnt vmcnt(30)
	ds_write_b32 v234, v151 offset:264
	s_waitcnt vmcnt(29)
	ds_write_b32 v234, v152 offset:528
	s_waitcnt vmcnt(28)
	ds_write_b32 v234, v153 offset:792
	s_waitcnt vmcnt(27)
	ds_write_b32 v234, v154 offset:1056
	s_waitcnt vmcnt(26)
	ds_write_b32 v234, v155 offset:1320
	s_waitcnt vmcnt(25)
	ds_write_b32 v234, v156 offset:1584
	s_waitcnt vmcnt(24)
	ds_write_b32 v234, v157 offset:1848
	s_waitcnt vmcnt(23)
	ds_write_b32 v234, v158 offset:2112
	s_waitcnt vmcnt(22)
	ds_write_b32 v234, v159 offset:2376
	s_waitcnt vmcnt(21)
	ds_write_b32 v234, v160 offset:2640
	s_waitcnt vmcnt(20)
	ds_write_b32 v234, v161 offset:2904
	s_waitcnt vmcnt(19)
	ds_write_b32 v234, v162 offset:3168
	s_waitcnt vmcnt(18)
	ds_write_b32 v234, v163 offset:3432
	s_waitcnt vmcnt(17)
	ds_write_b32 v234, v164 offset:3696
	s_waitcnt vmcnt(16)
	ds_write_b32 v234, v165 offset:3960
	s_waitcnt vmcnt(15)
	ds_write_b32 v234, v166 offset:4224
	s_waitcnt vmcnt(14)
	ds_write_b32 v234, v167 offset:4488
	s_waitcnt vmcnt(13)
	ds_write_b32 v234, v168 offset:4752
	s_waitcnt vmcnt(12)
	ds_write_b32 v234, v169 offset:5016
	s_waitcnt vmcnt(11)
	ds_write_b32 v234, v170 offset:5280
	s_waitcnt vmcnt(10)
	ds_write_b32 v234, v171 offset:5544
	s_waitcnt vmcnt(9)
	ds_write_b32 v234, v172 offset:5808
	s_waitcnt vmcnt(8)
	ds_write_b32 v234, v173 offset:6072
	s_waitcnt vmcnt(7)
	ds_write_b32 v234, v174 offset:6336
	s_waitcnt vmcnt(6)
	ds_write_b32 v234, v175 offset:6600
	s_waitcnt vmcnt(5)
	ds_write_b32 v234, v176 offset:6864
	s_waitcnt vmcnt(4)
	ds_write_b32 v234, v177 offset:7128
	s_waitcnt vmcnt(3)
	ds_write_b32 v234, v178 offset:7392
	s_waitcnt vmcnt(2)
	ds_write_b32 v234, v179 offset:7656
	s_waitcnt vmcnt(1)
	ds_write_b32 v234, v180 offset:7920
	s_waitcnt vmcnt(0)
	ds_write_b32 v234, v181 offset:8184
	s_mov_b32 s10, 0x40000
	v_add_u32_e32 v38, 0x2100, v38
	s_waitcnt lgkmcnt(0)
	ds_read2_b32 v[12:13], v26 offset0:33 offset1:41
	ds_read2_b32 v[14:15], v26 offset1:8
	ds_read2_b32 v[16:17], v26 offset0:66 offset1:74
	ds_read2_b32 v[18:19], v26 offset0:99 offset1:107
	ds_read2_b32 v[20:21], v26 offset0:132 offset1:140
	ds_read2_b32 v[22:23], v26 offset0:165 offset1:173
	ds_read2_b32 v[38:39], v26 offset0:198 offset1:206
	ds_read2_b32 v[40:41], v26 offset0:231 offset1:239
	s_lshl_b32 s8, s33, 5
	s_and_b32 s10, s8, 0x3e0
	s_lshl_b32 s8, s33, 2
	s_and_b32 s8, s8, 0x380
	s_waitcnt lgkmcnt(6)
	v_cvt_pk_bf16_f32 v8, v14, v12
	v_or_b32_e32 v12, s10, v25
	v_lshl_add_u64 v[42:43], v[2:3], 0, s[8:9]
	v_lshlrev_b32_e32 v44, 9, v12
	v_mov_b32_e32 v45, v1
	s_waitcnt lgkmcnt(4)
	v_cvt_pk_bf16_f32 v9, v16, v18
	s_waitcnt lgkmcnt(2)
	v_cvt_pk_bf16_f32 v10, v20, v22
	s_waitcnt lgkmcnt(0)
	v_cvt_pk_bf16_f32 v11, v38, v40
	v_lshl_add_u64 v[44:45], v[42:43], 0, v[44:45]
	global_store_dwordx4 v[44:45], v[8:11], off
	v_or_b32_e32 v12, s10, v27
	v_lshlrev_b32_e32 v12, 9, v12
	v_cvt_pk_bf16_f32 v8, v15, v13
	v_cvt_pk_bf16_f32 v9, v17, v19
	v_cvt_pk_bf16_f32 v10, v21, v23
	v_cvt_pk_bf16_f32 v11, v39, v41
	ds_read2_b32 v[14:15], v26 offset0:49 offset1:57
	ds_read2_b32 v[16:17], v26 offset0:16 offset1:24
	ds_read2_b32 v[18:19], v26 offset0:82 offset1:90
	ds_read2_b32 v[20:21], v26 offset0:115 offset1:123
	ds_read2_b32 v[22:23], v26 offset0:148 offset1:156
	ds_read2_b32 v[38:39], v26 offset0:181 offset1:189
	ds_read2_b32 v[40:41], v26 offset0:214 offset1:222
	ds_read2_b32 v[44:45], v26 offset0:247 offset1:255
	v_mov_b32_e32 v13, v1
	v_lshl_add_u64 v[12:13], v[42:43], 0, v[12:13]
	global_store_dwordx4 v[12:13], v[8:11], off
	v_or_b32_e32 v12, s10, v28
	v_lshlrev_b32_e32 v12, 9, v12
	v_mov_b32_e32 v13, v1
	s_waitcnt lgkmcnt(6)
	v_cvt_pk_bf16_f32 v8, v16, v14
	s_waitcnt lgkmcnt(4)
	v_cvt_pk_bf16_f32 v9, v18, v20
	s_waitcnt lgkmcnt(2)
	v_cvt_pk_bf16_f32 v10, v22, v38
	s_waitcnt lgkmcnt(0)
	v_cvt_pk_bf16_f32 v11, v40, v44
	v_lshl_add_u64 v[12:13], v[42:43], 0, v[12:13]
	global_store_dwordx4 v[12:13], v[8:11], off
	v_or_b32_e32 v12, s10, v29
	v_lshlrev_b32_e32 v12, 9, v12
	v_mov_b32_e32 v13, v1
	v_cvt_pk_bf16_f32 v8, v17, v15
	v_cvt_pk_bf16_f32 v9, v19, v21
	v_cvt_pk_bf16_f32 v10, v23, v39
	v_cvt_pk_bf16_f32 v11, v41, v45
	v_lshl_add_u64 v[12:13], v[42:43], 0, v[12:13]
	global_store_dwordx4 v[12:13], v[8:11], off
	s_waitcnt lgkmcnt(0)
	s_mov_b64 s[10:11], 0
.LBB0_1038:
	s_and_b64 vcc, exec, s[10:11]
	s_cbranch_vccz .LBB0_1033
	s_ashr_i32 s8, s33, 31
	s_lshr_b32 s8, s8, 27
	s_add_i32 s8, s33, s8
	s_load_dwordx2 s[18:19], s[0:1], 0x30
	s_and_b32 s10, s8, 0x7ffffe0
	s_sub_i32 s10, s33, s10
	s_lshl_b32 s10, s10, 5
	s_lshl_b32 s8, s8, 1
	s_ashr_i32 s11, s10, 31
	s_and_b32 s12, s8, 0xffffffc0
	s_lshl_b64 s[20:21], s[10:11], 2
	s_waitcnt lgkmcnt(0)
	s_add_u32 s18, s18, s20
	s_addc_u32 s19, s19, s21
	v_lshl_add_u64 v[8:9], s[18:19], 0, v[0:1]
	v_or_b32_e32 v10, s12, v24
	s_mov_b32 s8, 0
	v_mov_b32_e32 v11, v30
	v_mov_b32_e32 v230, v10
	v_mov_b32_e32 v231, 0
	v_lshl_add_u64 v[232:233], v[230:231], 2, s[4:5]
	v_lshlrev_b64 v[230:231], 12, v[230:231]
	v_lshl_add_u64 v[230:231], v[8:9], 0, v[230:231]
	v_mov_b32_e32 v234, v11
	s_mov_b32 s70, 0x2000
	s_mov_b32 s71, 0
	global_load_dword v150, v[230:231], off nt
	v_lshl_add_u64 v[230:231], v[230:231], 0, s[70:71]
	global_load_dword v151, v[230:231], off nt
	v_lshl_add_u64 v[230:231], v[230:231], 0, s[70:71]
	global_load_dword v152, v[230:231], off nt
	v_lshl_add_u64 v[230:231], v[230:231], 0, s[70:71]
	global_load_dword v153, v[230:231], off nt
	v_lshl_add_u64 v[230:231], v[230:231], 0, s[70:71]
	global_load_dword v154, v[230:231], off nt
	v_lshl_add_u64 v[230:231], v[230:231], 0, s[70:71]
	global_load_dword v155, v[230:231], off nt
	v_lshl_add_u64 v[230:231], v[230:231], 0, s[70:71]
	global_load_dword v156, v[230:231], off nt
	v_lshl_add_u64 v[230:231], v[230:231], 0, s[70:71]
	global_load_dword v157, v[230:231], off nt
	v_lshl_add_u64 v[230:231], v[230:231], 0, s[70:71]
	global_load_dword v158, v[230:231], off nt
	v_lshl_add_u64 v[230:231], v[230:231], 0, s[70:71]
	global_load_dword v159, v[230:231], off nt
	v_lshl_add_u64 v[230:231], v[230:231], 0, s[70:71]
	global_load_dword v160, v[230:231], off nt
	v_lshl_add_u64 v[230:231], v[230:231], 0, s[70:71]
	global_load_dword v161, v[230:231], off nt
	v_lshl_add_u64 v[230:231], v[230:231], 0, s[70:71]
	global_load_dword v162, v[230:231], off nt
	v_lshl_add_u64 v[230:231], v[230:231], 0, s[70:71]
	global_load_dword v163, v[230:231], off nt
	v_lshl_add_u64 v[230:231], v[230:231], 0, s[70:71]
	global_load_dword v164, v[230:231], off nt
	v_lshl_add_u64 v[230:231], v[230:231], 0, s[70:71]
	global_load_dword v165, v[230:231], off nt
	v_lshl_add_u64 v[230:231], v[230:231], 0, s[70:71]
	global_load_dword v166, v[230:231], off nt
	v_lshl_add_u64 v[230:231], v[230:231], 0, s[70:71]
	global_load_dword v167, v[230:231], off nt
	v_lshl_add_u64 v[230:231], v[230:231], 0, s[70:71]
	global_load_dword v168, v[230:231], off nt
	v_lshl_add_u64 v[230:231], v[230:231], 0, s[70:71]
	global_load_dword v169, v[230:231], off nt
	v_lshl_add_u64 v[230:231], v[230:231], 0, s[70:71]
	global_load_dword v170, v[230:231], off nt
	v_lshl_add_u64 v[230:231], v[230:231], 0, s[70:71]
	global_load_dword v171, v[230:231], off nt
	v_lshl_add_u64 v[230:231], v[230:231], 0, s[70:71]
	global_load_dword v172, v[230:231], off nt
	v_lshl_add_u64 v[230:231], v[230:231], 0, s[70:71]
	global_load_dword v173, v[230:231], off nt
	v_lshl_add_u64 v[230:231], v[230:231], 0, s[70:71]
	global_load_dword v174, v[230:231], off nt
	v_lshl_add_u64 v[230:231], v[230:231], 0, s[70:71]
	global_load_dword v175, v[230:231], off nt
	v_lshl_add_u64 v[230:231], v[230:231], 0, s[70:71]
	global_load_dword v176, v[230:231], off nt
	v_lshl_add_u64 v[230:231], v[230:231], 0, s[70:71]
	global_load_dword v177, v[230:231], off nt
	v_lshl_add_u64 v[230:231], v[230:231], 0, s[70:71]
	global_load_dword v178, v[230:231], off nt
	v_lshl_add_u64 v[230:231], v[230:231], 0, s[70:71]
	global_load_dword v179, v[230:231], off nt
	v_lshl_add_u64 v[230:231], v[230:231], 0, s[70:71]
	global_load_dword v180, v[230:231], off nt
	v_lshl_add_u64 v[230:231], v[230:231], 0, s[70:71]
	global_load_dword v181, v[230:231], off nt
	global_load_dword v182, v[232:233], off
	global_load_dword v183, v[232:233], off offset:8
	global_load_dword v184, v[232:233], off offset:16
	global_load_dword v185, v[232:233], off offset:24
	global_load_dword v186, v[232:233], off offset:32
	global_load_dword v187, v[232:233], off offset:40
	global_load_dword v188, v[232:233], off offset:48
	global_load_dword v189, v[232:233], off offset:56
	global_load_dword v190, v[232:233], off offset:64
	global_load_dword v191, v[232:233], off offset:72
	global_load_dword v192, v[232:233], off offset:80
	global_load_dword v193, v[232:233], off offset:88
	global_load_dword v194, v[232:233], off offset:96
	global_load_dword v195, v[232:233], off offset:104
	global_load_dword v196, v[232:233], off offset:112
	global_load_dword v197, v[232:233], off offset:120
	s_waitcnt vmcnt(15)
	v_mul_f32_e32 v150, v150, v182
	ds_write_b32 v234, v150
	s_waitcnt vmcnt(14)
	v_mul_f32_e32 v151, v151, v183
	ds_write_b32 v234, v151 offset:264
	s_waitcnt vmcnt(13)
	v_mul_f32_e32 v152, v152, v184
	ds_write_b32 v234, v152 offset:528
	s_waitcnt vmcnt(12)
	v_mul_f32_e32 v153, v153, v185
	ds_write_b32 v234, v153 offset:792
	s_waitcnt vmcnt(11)
	v_mul_f32_e32 v154, v154, v186
	ds_write_b32 v234, v154 offset:1056
	s_waitcnt vmcnt(10)
	v_mul_f32_e32 v155, v155, v187
	ds_write_b32 v234, v155 offset:1320
	s_waitcnt vmcnt(9)
	v_mul_f32_e32 v156, v156, v188
	ds_write_b32 v234, v156 offset:1584
	s_waitcnt vmcnt(8)
	v_mul_f32_e32 v157, v157, v189
	ds_write_b32 v234, v157 offset:1848
	s_waitcnt vmcnt(7)
	v_mul_f32_e32 v158, v158, v190
	ds_write_b32 v234, v158 offset:2112
	s_waitcnt vmcnt(6)
	v_mul_f32_e32 v159, v159, v191
	ds_write_b32 v234, v159 offset:2376
	s_waitcnt vmcnt(5)
	v_mul_f32_e32 v160, v160, v192
	ds_write_b32 v234, v160 offset:2640
	s_waitcnt vmcnt(4)
	v_mul_f32_e32 v161, v161, v193
	ds_write_b32 v234, v161 offset:2904
	s_waitcnt vmcnt(3)
	v_mul_f32_e32 v162, v162, v194
	ds_write_b32 v234, v162 offset:3168
	s_waitcnt vmcnt(2)
	v_mul_f32_e32 v163, v163, v195
	ds_write_b32 v234, v163 offset:3432
	s_waitcnt vmcnt(1)
	v_mul_f32_e32 v164, v164, v196
	ds_write_b32 v234, v164 offset:3696
	s_waitcnt vmcnt(0)
	v_mul_f32_e32 v165, v165, v197
	ds_write_b32 v234, v165 offset:3960
	global_load_dword v182, v[232:233], off offset:128
	global_load_dword v183, v[232:233], off offset:136
	global_load_dword v184, v[232:233], off offset:144
	global_load_dword v185, v[232:233], off offset:152
	global_load_dword v186, v[232:233], off offset:160
	global_load_dword v187, v[232:233], off offset:168
	global_load_dword v188, v[232:233], off offset:176
	global_load_dword v189, v[232:233], off offset:184
	global_load_dword v190, v[232:233], off offset:192
	global_load_dword v191, v[232:233], off offset:200
	global_load_dword v192, v[232:233], off offset:208
	global_load_dword v193, v[232:233], off offset:216
	global_load_dword v194, v[232:233], off offset:224
	global_load_dword v195, v[232:233], off offset:232
	global_load_dword v196, v[232:233], off offset:240
	global_load_dword v197, v[232:233], off offset:248
	s_waitcnt vmcnt(15)
	v_mul_f32_e32 v166, v166, v182
	ds_write_b32 v234, v166 offset:4224
	s_waitcnt vmcnt(14)
	v_mul_f32_e32 v167, v167, v183
	ds_write_b32 v234, v167 offset:4488
	s_waitcnt vmcnt(13)
	v_mul_f32_e32 v168, v168, v184
	ds_write_b32 v234, v168 offset:4752
	s_waitcnt vmcnt(12)
	v_mul_f32_e32 v169, v169, v185
	ds_write_b32 v234, v169 offset:5016
	s_waitcnt vmcnt(11)
	v_mul_f32_e32 v170, v170, v186
	ds_write_b32 v234, v170 offset:5280
	s_waitcnt vmcnt(10)
	v_mul_f32_e32 v171, v171, v187
	ds_write_b32 v234, v171 offset:5544
	s_waitcnt vmcnt(9)
	v_mul_f32_e32 v172, v172, v188
	ds_write_b32 v234, v172 offset:5808
	s_waitcnt vmcnt(8)
	v_mul_f32_e32 v173, v173, v189
	ds_write_b32 v234, v173 offset:6072
	s_waitcnt vmcnt(7)
	v_mul_f32_e32 v174, v174, v190
	ds_write_b32 v234, v174 offset:6336
	s_waitcnt vmcnt(6)
	v_mul_f32_e32 v175, v175, v191
	ds_write_b32 v234, v175 offset:6600
	s_waitcnt vmcnt(5)
	v_mul_f32_e32 v176, v176, v192
	ds_write_b32 v234, v176 offset:6864
	s_waitcnt vmcnt(4)
	v_mul_f32_e32 v177, v177, v193
	ds_write_b32 v234, v177 offset:7128
	s_waitcnt vmcnt(3)
	v_mul_f32_e32 v178, v178, v194
	ds_write_b32 v234, v178 offset:7392
	s_waitcnt vmcnt(2)
	v_mul_f32_e32 v179, v179, v195
	ds_write_b32 v234, v179 offset:7656
	s_waitcnt vmcnt(1)
	v_mul_f32_e32 v180, v180, v196
	ds_write_b32 v234, v180 offset:7920
	s_waitcnt vmcnt(0)
	v_mul_f32_e32 v181, v181, v197
	ds_write_b32 v234, v181 offset:8184
	s_mov_b32 s8, 0x40
	v_add_u32_e32 v11, 0x2100, v11
	s_waitcnt lgkmcnt(0)
	ds_read2_b32 v[12:13], v26 offset0:33 offset1:41
	ds_read2_b32 v[14:15], v26 offset1:8
	ds_read2_b32 v[16:17], v26 offset0:66 offset1:74
	ds_read2_b32 v[18:19], v26 offset0:99 offset1:107
	ds_read2_b32 v[20:21], v26 offset0:132 offset1:140
	ds_read2_b32 v[22:23], v26 offset0:165 offset1:173
	ds_read2_b32 v[38:39], v26 offset0:198 offset1:206
	ds_read2_b32 v[40:41], v26 offset0:231 offset1:239
	v_or_b32_e32 v44, s10, v25
	s_ashr_i32 s13, s12, 31
	v_ashrrev_i32_e32 v45, 31, v44
	v_lshl_add_u64 v[42:43], s[12:13], 1, v[4:5]
	v_lshlrev_b64 v[44:45], 11, v[44:45]
	s_waitcnt lgkmcnt(6)
	v_cvt_pk_bf16_f32 v8, v14, v12
	s_waitcnt lgkmcnt(4)
	v_cvt_pk_bf16_f32 v9, v16, v18
	s_waitcnt lgkmcnt(2)
	v_cvt_pk_bf16_f32 v10, v20, v22
	s_waitcnt lgkmcnt(0)
	v_cvt_pk_bf16_f32 v11, v38, v40
	v_lshl_add_u64 v[44:45], v[42:43], 0, v[44:45]
	v_or_b32_e32 v12, s10, v27
	global_store_dwordx4 v[44:45], v[8:11], off
	s_nop 1
	v_cvt_pk_bf16_f32 v8, v15, v13
	v_ashrrev_i32_e32 v13, 31, v12
	v_cvt_pk_bf16_f32 v9, v17, v19
	v_cvt_pk_bf16_f32 v10, v21, v23
	v_cvt_pk_bf16_f32 v11, v39, v41
	v_lshlrev_b64 v[12:13], 11, v[12:13]
	ds_read2_b32 v[14:15], v26 offset0:49 offset1:57
	ds_read2_b32 v[16:17], v26 offset0:16 offset1:24
	ds_read2_b32 v[18:19], v26 offset0:82 offset1:90
	ds_read2_b32 v[20:21], v26 offset0:115 offset1:123
	ds_read2_b32 v[22:23], v26 offset0:148 offset1:156
	ds_read2_b32 v[38:39], v26 offset0:181 offset1:189
	ds_read2_b32 v[40:41], v26 offset0:214 offset1:222
	ds_read2_b32 v[44:45], v26 offset0:247 offset1:255
	v_lshl_add_u64 v[12:13], v[42:43], 0, v[12:13]
	global_store_dwordx4 v[12:13], v[8:11], off
	v_or_b32_e32 v12, s10, v28
	v_ashrrev_i32_e32 v13, 31, v12
	v_lshlrev_b64 v[12:13], 11, v[12:13]
	s_waitcnt lgkmcnt(6)
	v_cvt_pk_bf16_f32 v8, v16, v14
	s_waitcnt lgkmcnt(4)
	v_cvt_pk_bf16_f32 v9, v18, v20
	s_waitcnt lgkmcnt(2)
	v_cvt_pk_bf16_f32 v10, v22, v38
	s_waitcnt lgkmcnt(0)
	v_cvt_pk_bf16_f32 v11, v40, v44
	v_lshl_add_u64 v[12:13], v[42:43], 0, v[12:13]
	global_store_dwordx4 v[12:13], v[8:11], off
	v_or_b32_e32 v12, s10, v29
	v_ashrrev_i32_e32 v13, 31, v12
	v_lshlrev_b64 v[12:13], 11, v[12:13]
	v_cvt_pk_bf16_f32 v8, v17, v15
	v_cvt_pk_bf16_f32 v9, v19, v21
	v_cvt_pk_bf16_f32 v10, v23, v39
	v_cvt_pk_bf16_f32 v11, v41, v45
	v_lshl_add_u64 v[12:13], v[42:43], 0, v[12:13]
	global_store_dwordx4 v[12:13], v[8:11], off
	s_waitcnt lgkmcnt(0)
	s_branch .LBB0_1033

.LBB0_1209:
	s_cmpk_gt_i32 s33, 0xaff
	s_mov_b64 s[12:13], -1
	s_cbranch_scc0 .LBB0_1213
	s_lshl_b32 s8, s18, 2
	s_and_b32 s14, s20, 0x1ffc0
	s_and_b32 s8, s8, 0xf80
	v_or_b32_e32 v10, s14, v50
	v_lshl_or_b32 v12, v10, 12, s8
	v_or_b32_e32 v10, s14, v51
	v_lshl_or_b32 v14, v10, 12, s8
	v_or_b32_e32 v10, s14, v52
	s_load_dwordx2 s[12:13], s[0:1], 0x20
	v_lshl_or_b32 v16, v10, 12, s8
	v_or_b32_e32 v10, s14, v53
	v_lshl_or_b32 v18, v10, 12, s8
	v_or_b32_e32 v10, s14, v54
	v_lshl_or_b32 v20, v10, 12, s8
	v_or_b32_e32 v10, s14, v55
	v_or_b32_e32 v0, s14, v49
	v_lshl_or_b32 v22, v10, 12, s8
	v_or_b32_e32 v10, s14, v42
	v_lshl_or_b32 v0, v0, 12, s8
	v_mov_b32_e32 v13, v1
	v_mov_b32_e32 v15, v1
	v_mov_b32_e32 v17, v1
	v_mov_b32_e32 v19, v1
	v_mov_b32_e32 v21, v1
	v_mov_b32_e32 v23, v1
	v_lshl_or_b32 v24, v10, 12, s8
	v_mov_b32_e32 v25, v1
	s_waitcnt lgkmcnt(0)
	v_lshl_add_u64 v[26:27], s[12:13], 0, v[8:9]
	v_lshl_add_u64 v[10:11], v[26:27], 0, v[0:1]
	v_lshl_add_u64 v[12:13], v[26:27], 0, v[12:13]
	v_lshl_add_u64 v[14:15], v[26:27], 0, v[14:15]
	v_lshl_add_u64 v[16:17], v[26:27], 0, v[16:17]
	v_lshl_add_u64 v[18:19], v[26:27], 0, v[18:19]
	v_lshl_add_u64 v[20:21], v[26:27], 0, v[20:21]
	v_lshl_add_u64 v[22:23], v[26:27], 0, v[22:23]
	v_lshl_add_u64 v[24:25], v[26:27], 0, v[24:25]
	s_mov_b64 s[12:13], 0
	v_mov_b32_e32 v0, v48
	v_mov_b32_e32 v230, v24
	v_mov_b32_e32 v231, v25
	v_mov_b32_e32 v234, v0
	s_mov_b32 s58, 0x2000
	s_mov_b32 s59, 0
	global_load_dword v150, v[230:231], off nt
	v_lshl_add_u64 v[230:231], v[230:231], 0, s[58:59]
	global_load_dword v151, v[230:231], off nt
	v_lshl_add_u64 v[230:231], v[230:231], 0, s[58:59]
	global_load_dword v152, v[230:231], off nt
	v_lshl_add_u64 v[230:231], v[230:231], 0, s[58:59]
	global_load_dword v153, v[230:231], off nt
	v_lshl_add_u64 v[230:231], v[230:231], 0, s[58:59]
	global_load_dword v154, v[230:231], off nt
	v_lshl_add_u64 v[230:231], v[230:231], 0, s[58:59]
	global_load_dword v155, v[230:231], off nt
	v_lshl_add_u64 v[230:231], v[230:231], 0, s[58:59]
	global_load_dword v156, v[230:231], off nt
	v_lshl_add_u64 v[230:231], v[230:231], 0, s[58:59]
	global_load_dword v157, v[230:231], off nt
	v_lshl_add_u64 v[230:231], v[230:231], 0, s[58:59]
	global_load_dword v158, v[230:231], off nt
	v_lshl_add_u64 v[230:231], v[230:231], 0, s[58:59]
	global_load_dword v159, v[230:231], off nt
	v_lshl_add_u64 v[230:231], v[230:231], 0, s[58:59]
	global_load_dword v160, v[230:231], off nt
	v_lshl_add_u64 v[230:231], v[230:231], 0, s[58:59]
	global_load_dword v161, v[230:231], off nt
	v_lshl_add_u64 v[230:231], v[230:231], 0, s[58:59]
	global_load_dword v162, v[230:231], off nt
	v_lshl_add_u64 v[230:231], v[230:231], 0, s[58:59]
	global_load_dword v163, v[230:231], off nt
	v_lshl_add_u64 v[230:231], v[230:231], 0, s[58:59]
	global_load_dword v164, v[230:231], off nt
	v_lshl_add_u64 v[230:231], v[230:231], 0, s[58:59]
	global_load_dword v165, v[230:231], off nt
	v_lshl_add_u64 v[230:231], v[230:231], 0, s[58:59]
	global_load_dword v166, v[230:231], off nt
	v_lshl_add_u64 v[230:231], v[230:231], 0, s[58:59]
	global_load_dword v167, v[230:231], off nt
	v_lshl_add_u64 v[230:231], v[230:231], 0, s[58:59]
	global_load_dword v168, v[230:231], off nt
	v_lshl_add_u64 v[230:231], v[230:231], 0, s[58:59]
	global_load_dword v169, v[230:231], off nt
	v_lshl_add_u64 v[230:231], v[230:231], 0, s[58:59]
	global_load_dword v170, v[230:231], off nt
	v_lshl_add_u64 v[230:231], v[230:231], 0, s[58:59]
	global_load_dword v171, v[230:231], off nt
	v_lshl_add_u64 v[230:231], v[230:231], 0, s[58:59]
	global_load_dword v172, v[230:231], off nt
	v_lshl_add_u64 v[230:231], v[230:231], 0, s[58:59]
	global_load_dword v173, v[230:231], off nt
	v_lshl_add_u64 v[230:231], v[230:231], 0, s[58:59]
	global_load_dword v174, v[230:231], off nt
	v_lshl_add_u64 v[230:231], v[230:231], 0, s[58:59]
	global_load_dword v175, v[230:231], off nt
	v_lshl_add_u64 v[230:231], v[230:231], 0, s[58:59]
	global_load_dword v176, v[230:231], off nt
	v_lshl_add_u64 v[230:231], v[230:231], 0, s[58:59]
	global_load_dword v177, v[230:231], off nt
	v_lshl_add_u64 v[230:231], v[230:231], 0, s[58:59]
	global_load_dword v178, v[230:231], off nt
	v_lshl_add_u64 v[230:231], v[230:231], 0, s[58:59]
	global_load_dword v179, v[230:231], off nt
	v_lshl_add_u64 v[230:231], v[230:231], 0, s[58:59]
	global_load_dword v180, v[230:231], off nt
	v_lshl_add_u64 v[230:231], v[230:231], 0, s[58:59]
	global_load_dword v181, v[230:231], off nt
	s_waitcnt vmcnt(31)
	ds_write_b32 v234, v150
	s_waitcnt vmcnt(30)
	ds_write_b32 v234, v151 offset:264
	s_waitcnt vmcnt(29)
	ds_write_b32 v234, v152 offset:528
	s_waitcnt vmcnt(28)
	ds_write_b32 v234, v153 offset:792
	s_waitcnt vmcnt(27)
	ds_write_b32 v234, v154 offset:1056
	s_waitcnt vmcnt(26)
	ds_write_b32 v234, v155 offset:1320
	s_waitcnt vmcnt(25)
	ds_write_b32 v234, v156 offset:1584
	s_waitcnt vmcnt(24)
	ds_write_b32 v234, v157 offset:1848
	s_waitcnt vmcnt(23)
	ds_write_b32 v234, v158 offset:2112
	s_waitcnt vmcnt(22)
	ds_write_b32 v234, v159 offset:2376
	s_waitcnt vmcnt(21)
	ds_write_b32 v234, v160 offset:2640
	s_waitcnt vmcnt(20)
	ds_write_b32 v234, v161 offset:2904
	s_waitcnt vmcnt(19)
	ds_write_b32 v234, v162 offset:3168
	s_waitcnt vmcnt(18)
	ds_write_b32 v234, v163 offset:3432
	s_waitcnt vmcnt(17)
	ds_write_b32 v234, v164 offset:3696
	s_waitcnt vmcnt(16)
	ds_write_b32 v234, v165 offset:3960
	s_waitcnt vmcnt(15)
	ds_write_b32 v234, v166 offset:4224
	s_waitcnt vmcnt(14)
	ds_write_b32 v234, v167 offset:4488
	s_waitcnt vmcnt(13)
	ds_write_b32 v234, v168 offset:4752
	s_waitcnt vmcnt(12)
	ds_write_b32 v234, v169 offset:5016
	s_waitcnt vmcnt(11)
	ds_write_b32 v234, v170 offset:5280
	s_waitcnt vmcnt(10)
	ds_write_b32 v234, v171 offset:5544
	s_waitcnt vmcnt(9)
	ds_write_b32 v234, v172 offset:5808
	s_waitcnt vmcnt(8)
	ds_write_b32 v234, v173 offset:6072
	s_waitcnt vmcnt(7)
	ds_write_b32 v234, v174 offset:6336
	s_waitcnt vmcnt(6)
	ds_write_b32 v234, v175 offset:6600
	s_waitcnt vmcnt(5)
	ds_write_b32 v234, v176 offset:6864
	s_waitcnt vmcnt(4)
	ds_write_b32 v234, v177 offset:7128
	s_waitcnt vmcnt(3)
	ds_write_b32 v234, v178 offset:7392
	s_waitcnt vmcnt(2)
	ds_write_b32 v234, v179 offset:7656
	s_waitcnt vmcnt(1)
	ds_write_b32 v234, v180 offset:7920
	s_waitcnt vmcnt(0)
	ds_write_b32 v234, v181 offset:8184
	s_mov_b32 s12, 0x40000
	v_add_u32_e32 v0, 0x2100, v0
	s_waitcnt lgkmcnt(0)
	s_lshl_b32 s8, s33, 1
	s_lshl_b32 s12, s33, 5
	s_add_i32 s8, s8, 0x1ea00
	s_and_b32 s12, s12, 0x3e0
	ds_read2_b32 v[14:15], v44 offset0:33 offset1:41
	ds_read2_b32 v[16:17], v44 offset1:8
	ds_read2_b32 v[18:19], v44 offset0:66 offset1:74
	ds_read2_b32 v[20:21], v44 offset0:99 offset1:107
	ds_read2_b32 v[22:23], v44 offset0:132 offset1:140
	ds_read2_b32 v[24:25], v44 offset0:165 offset1:173
	ds_read2_b32 v[26:27], v44 offset0:198 offset1:206
	ds_read2_b32 v[28:29], v44 offset0:231 offset1:239
	s_and_b32 s8, s8, 0x1ffc0
	v_or_b32_e32 v0, s12, v43
	s_lshl_b32 s8, s8, 1
	v_mul_u32_u24_e32 v0, 0xb00, v0
	v_lshl_add_u64 v[30:31], v[2:3], 0, s[8:9]
	v_lshlrev_b32_e32 v0, 1, v0
	v_lshl_add_u64 v[32:33], v[30:31], 0, v[0:1]
	v_or_b32_e32 v0, s12, v45
	s_waitcnt lgkmcnt(6)
	v_cvt_pk_bf16_f32 v10, v16, v14
	s_waitcnt lgkmcnt(4)
	v_cvt_pk_bf16_f32 v11, v18, v20
	s_waitcnt lgkmcnt(2)
	v_cvt_pk_bf16_f32 v12, v22, v24
	s_waitcnt lgkmcnt(0)
	v_cvt_pk_bf16_f32 v13, v26, v28
	v_mul_u32_u24_e32 v0, 0xb00, v0
	global_store_dwordx4 v[32:33], v[10:13], off
	v_lshlrev_b32_e32 v0, 1, v0
	s_nop 0
	v_cvt_pk_bf16_f32 v10, v17, v15
	v_cvt_pk_bf16_f32 v11, v19, v21
	v_cvt_pk_bf16_f32 v12, v23, v25
	v_cvt_pk_bf16_f32 v13, v27, v29
	v_lshl_add_u64 v[14:15], v[30:31], 0, v[0:1]
	ds_read2_b32 v[16:17], v44 offset0:16 offset1:24
	ds_read2_b32 v[18:19], v44 offset0:49 offset1:57
	ds_read2_b32 v[20:21], v44 offset0:82 offset1:90
	ds_read2_b32 v[22:23], v44 offset0:115 offset1:123
	ds_read2_b32 v[24:25], v44 offset0:148 offset1:156
	ds_read2_b32 v[26:27], v44 offset0:181 offset1:189
	ds_read2_b32 v[28:29], v44 offset0:214 offset1:222
	ds_read2_b32 v[32:33], v44 offset0:247 offset1:255
	v_or_b32_e32 v0, s12, v46
	v_mul_u32_u24_e32 v0, 0xb00, v0
	v_lshlrev_b32_e32 v0, 1, v0
	global_store_dwordx4 v[14:15], v[10:13], off
	v_lshl_add_u64 v[14:15], v[30:31], 0, v[0:1]
	v_or_b32_e32 v0, s12, v47
	v_mul_u32_u24_e32 v0, 0xb00, v0
	s_waitcnt lgkmcnt(6)
	v_cvt_pk_bf16_f32 v10, v16, v18
	s_waitcnt lgkmcnt(4)
	v_cvt_pk_bf16_f32 v11, v20, v22
	s_waitcnt lgkmcnt(2)
	v_cvt_pk_bf16_f32 v12, v24, v26
	s_waitcnt lgkmcnt(0)
	v_cvt_pk_bf16_f32 v13, v28, v32
	v_lshlrev_b32_e32 v0, 1, v0
	global_store_dwordx4 v[14:15], v[10:13], off
	v_lshl_add_u64 v[14:15], v[30:31], 0, v[0:1]
	s_mov_b64 s[12:13], 0
	v_cvt_pk_bf16_f32 v10, v17, v19
	v_cvt_pk_bf16_f32 v11, v21, v23
	v_cvt_pk_bf16_f32 v12, v25, v27
	v_cvt_pk_bf16_f32 v13, v29, v33
	global_store_dwordx4 v[14:15], v[10:13], off
	s_waitcnt lgkmcnt(0)
.LBB0_1213:
	s_and_b64 vcc, exec, s[12:13]
	s_cbranch_vccz .LBB0_1208
	s_mul_hi_i32 s8, s33, 0x2e8ba2e9
	s_lshr_b32 s12, s8, 31
	s_ashr_i32 s8, s8, 5
	s_add_i32 s12, s8, s12
	s_load_dwordx2 s[16:17], s[0:1], 0x18
	s_mul_i32 s8, s12, 0xb0
	s_sub_i32 s8, s33, s8
	s_lshl_b32 s14, s8, 5
	s_ashr_i32 s15, s14, 31
	s_lshl_b32 s12, s12, 6
	s_lshl_b64 s[24:25], s[14:15], 2
	s_waitcnt lgkmcnt(0)
	s_add_u32 s13, s16, s24
	s_addc_u32 s15, s17, s25
	s_add_u32 s16, s13, 0x2c00000
	v_or_b32_e32 v12, s12, v49
	s_addc_u32 s17, s15, 0
	v_or_b32_e32 v16, s12, v50
	v_or_b32_e32 v20, s12, v51
	v_or_b32_e32 v24, s12, v52
	v_or_b32_e32 v28, s12, v53
	v_or_b32_e32 v32, s12, v54
	v_or_b32_e32 v36, s12, v55
	v_ashrrev_i32_e32 v13, 31, v12
	v_mov_b64_e32 v[40:41], s[16:17]
	v_ashrrev_i32_e32 v17, 31, v16
	v_ashrrev_i32_e32 v21, 31, v20
	v_ashrrev_i32_e32 v25, 31, v24
	v_ashrrev_i32_e32 v29, 31, v28
	v_ashrrev_i32_e32 v33, 31, v32
	v_ashrrev_i32_e32 v37, 31, v36
	v_or_b32_e32 v56, s12, v42
	v_lshl_add_u64 v[10:11], v[12:13], 2, s[4:5]
	v_mad_i64_i32 v[12:13], s[16:17], v12, s22, v[40:41]
	v_lshl_add_u64 v[14:15], v[16:17], 2, s[4:5]
	v_mad_i64_i32 v[16:17], s[16:17], v16, s22, v[40:41]
	v_lshl_add_u64 v[18:19], v[20:21], 2, s[4:5]
	v_mad_i64_i32 v[20:21], s[16:17], v20, s22, v[40:41]
	v_lshl_add_u64 v[22:23], v[24:25], 2, s[4:5]
	v_mad_i64_i32 v[24:25], s[16:17], v24, s22, v[40:41]
	v_lshl_add_u64 v[26:27], v[28:29], 2, s[4:5]
	v_mad_i64_i32 v[28:29], s[16:17], v28, s22, v[40:41]
	v_lshl_add_u64 v[30:31], v[32:33], 2, s[4:5]
	v_mad_i64_i32 v[32:33], s[16:17], v32, s22, v[40:41]
	v_lshl_add_u64 v[34:35], v[36:37], 2, s[4:5]
	v_mad_i64_i32 v[36:37], s[16:17], v36, s22, v[40:41]
	v_ashrrev_i32_e32 v57, 31, v56
	v_mad_i64_i32 v[40:41], s[16:17], v56, s22, v[40:41]
	v_lshl_add_u64 v[38:39], v[56:57], 2, s[4:5]
	s_mov_b64 s[16:17], 0
	v_mov_b32_e32 v0, v48
	v_lshl_add_u64 v[230:231], v[40:41], 0, v[6:7]
	v_mov_b32_e32 v232, v38
	v_mov_b32_e32 v233, v39
	v_mov_b32_e32 v234, v0
	s_mov_b32 s58, 0xb000
	s_mov_b32 s59, 0
	global_load_dword v150, v[230:231], off nt
	v_lshl_add_u64 v[230:231], v[230:231], 0, s[58:59]
	global_load_dword v151, v[230:231], off nt
	v_lshl_add_u64 v[230:231], v[230:231], 0, s[58:59]
	global_load_dword v152, v[230:231], off nt
	v_lshl_add_u64 v[230:231], v[230:231], 0, s[58:59]
	global_load_dword v153, v[230:231], off nt
	v_lshl_add_u64 v[230:231], v[230:231], 0, s[58:59]
	global_load_dword v154, v[230:231], off nt
	v_lshl_add_u64 v[230:231], v[230:231], 0, s[58:59]
	global_load_dword v155, v[230:231], off nt
	v_lshl_add_u64 v[230:231], v[230:231], 0, s[58:59]
	global_load_dword v156, v[230:231], off nt
	v_lshl_add_u64 v[230:231], v[230:231], 0, s[58:59]
	global_load_dword v157, v[230:231], off nt
	v_lshl_add_u64 v[230:231], v[230:231], 0, s[58:59]
	global_load_dword v158, v[230:231], off nt
	v_lshl_add_u64 v[230:231], v[230:231], 0, s[58:59]
	global_load_dword v159, v[230:231], off nt
	v_lshl_add_u64 v[230:231], v[230:231], 0, s[58:59]
	global_load_dword v160, v[230:231], off nt
	v_lshl_add_u64 v[230:231], v[230:231], 0, s[58:59]
	global_load_dword v161, v[230:231], off nt
	v_lshl_add_u64 v[230:231], v[230:231], 0, s[58:59]
	global_load_dword v162, v[230:231], off nt
	v_lshl_add_u64 v[230:231], v[230:231], 0, s[58:59]
	global_load_dword v163, v[230:231], off nt
	v_lshl_add_u64 v[230:231], v[230:231], 0, s[58:59]
	global_load_dword v164, v[230:231], off nt
	v_lshl_add_u64 v[230:231], v[230:231], 0, s[58:59]
	global_load_dword v165, v[230:231], off nt
	v_lshl_add_u64 v[230:231], v[230:231], 0, s[58:59]
	global_load_dword v166, v[230:231], off nt
	v_lshl_add_u64 v[230:231], v[230:231], 0, s[58:59]
	global_load_dword v167, v[230:231], off nt
	v_lshl_add_u64 v[230:231], v[230:231], 0, s[58:59]
	global_load_dword v168, v[230:231], off nt
	v_lshl_add_u64 v[230:231], v[230:231], 0, s[58:59]
	global_load_dword v169, v[230:231], off nt
	v_lshl_add_u64 v[230:231], v[230:231], 0, s[58:59]
	global_load_dword v170, v[230:231], off nt
	v_lshl_add_u64 v[230:231], v[230:231], 0, s[58:59]
	global_load_dword v171, v[230:231], off nt
	v_lshl_add_u64 v[230:231], v[230:231], 0, s[58:59]
	global_load_dword v172, v[230:231], off nt
	v_lshl_add_u64 v[230:231], v[230:231], 0, s[58:59]
	global_load_dword v173, v[230:231], off nt
	v_lshl_add_u64 v[230:231], v[230:231], 0, s[58:59]
	global_load_dword v174, v[230:231], off nt
	v_lshl_add_u64 v[230:231], v[230:231], 0, s[58:59]
	global_load_dword v175, v[230:231], off nt
	v_lshl_add_u64 v[230:231], v[230:231], 0, s[58:59]
	global_load_dword v176, v[230:231], off nt
	v_lshl_add_u64 v[230:231], v[230:231], 0, s[58:59]
	global_load_dword v177, v[230:231], off nt
	v_lshl_add_u64 v[230:231], v[230:231], 0, s[58:59]
	global_load_dword v178, v[230:231], off nt
	v_lshl_add_u64 v[230:231], v[230:231], 0, s[58:59]
	global_load_dword v179, v[230:231], off nt
	v_lshl_add_u64 v[230:231], v[230:231], 0, s[58:59]
	global_load_dword v180, v[230:231], off nt
	v_lshl_add_u64 v[230:231], v[230:231], 0, s[58:59]
	global_load_dword v181, v[230:231], off nt
	global_load_dword v182, v[232:233], off
	global_load_dword v183, v[232:233], off offset:8
	global_load_dword v184, v[232:233], off offset:16
	global_load_dword v185, v[232:233], off offset:24
	global_load_dword v186, v[232:233], off offset:32
	global_load_dword v187, v[232:233], off offset:40
	global_load_dword v188, v[232:233], off offset:48
	global_load_dword v189, v[232:233], off offset:56
	global_load_dword v190, v[232:233], off offset:64
	global_load_dword v191, v[232:233], off offset:72
	global_load_dword v192, v[232:233], off offset:80
	global_load_dword v193, v[232:233], off offset:88
	global_load_dword v194, v[232:233], off offset:96
	global_load_dword v195, v[232:233], off offset:104
	global_load_dword v196, v[232:233], off offset:112
	global_load_dword v197, v[232:233], off offset:120
	s_waitcnt vmcnt(15)
	v_mul_f32_e32 v150, v150, v182
	ds_write_b32 v234, v150
	s_waitcnt vmcnt(14)
	v_mul_f32_e32 v151, v151, v183
	ds_write_b32 v234, v151 offset:264
	s_waitcnt vmcnt(13)
	v_mul_f32_e32 v152, v152, v184
	ds_write_b32 v234, v152 offset:528
	s_waitcnt vmcnt(12)
	v_mul_f32_e32 v153, v153, v185
	ds_write_b32 v234, v153 offset:792
	s_waitcnt vmcnt(11)
	v_mul_f32_e32 v154, v154, v186
	ds_write_b32 v234, v154 offset:1056
	s_waitcnt vmcnt(10)
	v_mul_f32_e32 v155, v155, v187
	ds_write_b32 v234, v155 offset:1320
	s_waitcnt vmcnt(9)
	v_mul_f32_e32 v156, v156, v188
	ds_write_b32 v234, v156 offset:1584
	s_waitcnt vmcnt(8)
	v_mul_f32_e32 v157, v157, v189
	ds_write_b32 v234, v157 offset:1848
	s_waitcnt vmcnt(7)
	v_mul_f32_e32 v158, v158, v190
	ds_write_b32 v234, v158 offset:2112
	s_waitcnt vmcnt(6)
	v_mul_f32_e32 v159, v159, v191
	ds_write_b32 v234, v159 offset:2376
	s_waitcnt vmcnt(5)
	v_mul_f32_e32 v160, v160, v192
	ds_write_b32 v234, v160 offset:2640
	s_waitcnt vmcnt(4)
	v_mul_f32_e32 v161, v161, v193
	ds_write_b32 v234, v161 offset:2904
	s_waitcnt vmcnt(3)
	v_mul_f32_e32 v162, v162, v194
	ds_write_b32 v234, v162 offset:3168
	s_waitcnt vmcnt(2)
	v_mul_f32_e32 v163, v163, v195
	ds_write_b32 v234, v163 offset:3432
	s_waitcnt vmcnt(1)
	v_mul_f32_e32 v164, v164, v196
	ds_write_b32 v234, v164 offset:3696
	s_waitcnt vmcnt(0)
	v_mul_f32_e32 v165, v165, v197
	ds_write_b32 v234, v165 offset:3960
	global_load_dword v182, v[232:233], off offset:128
	global_load_dword v183, v[232:233], off offset:136
	global_load_dword v184, v[232:233], off offset:144
	global_load_dword v185, v[232:233], off offset:152
	global_load_dword v186, v[232:233], off offset:160
	global_load_dword v187, v[232:233], off offset:168
	global_load_dword v188, v[232:233], off offset:176
	global_load_dword v189, v[232:233], off offset:184
	global_load_dword v190, v[232:233], off offset:192
	global_load_dword v191, v[232:233], off offset:200
	global_load_dword v192, v[232:233], off offset:208
	global_load_dword v193, v[232:233], off offset:216
	global_load_dword v194, v[232:233], off offset:224
	global_load_dword v195, v[232:233], off offset:232
	global_load_dword v196, v[232:233], off offset:240
	global_load_dword v197, v[232:233], off offset:248
	s_waitcnt vmcnt(15)
	v_mul_f32_e32 v166, v166, v182
	ds_write_b32 v234, v166 offset:4224
	s_waitcnt vmcnt(14)
	v_mul_f32_e32 v167, v167, v183
	ds_write_b32 v234, v167 offset:4488
	s_waitcnt vmcnt(13)
	v_mul_f32_e32 v168, v168, v184
	ds_write_b32 v234, v168 offset:4752
	s_waitcnt vmcnt(12)
	v_mul_f32_e32 v169, v169, v185
	ds_write_b32 v234, v169 offset:5016
	s_waitcnt vmcnt(11)
	v_mul_f32_e32 v170, v170, v186
	ds_write_b32 v234, v170 offset:5280
	s_waitcnt vmcnt(10)
	v_mul_f32_e32 v171, v171, v187
	ds_write_b32 v234, v171 offset:5544
	s_waitcnt vmcnt(9)
	v_mul_f32_e32 v172, v172, v188
	ds_write_b32 v234, v172 offset:5808
	s_waitcnt vmcnt(8)
	v_mul_f32_e32 v173, v173, v189
	ds_write_b32 v234, v173 offset:6072
	s_waitcnt vmcnt(7)
	v_mul_f32_e32 v174, v174, v190
	ds_write_b32 v234, v174 offset:6336
	s_waitcnt vmcnt(6)
	v_mul_f32_e32 v175, v175, v191
	ds_write_b32 v234, v175 offset:6600
	s_waitcnt vmcnt(5)
	v_mul_f32_e32 v176, v176, v192
	ds_write_b32 v234, v176 offset:6864
	s_waitcnt vmcnt(4)
	v_mul_f32_e32 v177, v177, v193
	ds_write_b32 v234, v177 offset:7128
	s_waitcnt vmcnt(3)
	v_mul_f32_e32 v178, v178, v194
	ds_write_b32 v234, v178 offset:7392
	s_waitcnt vmcnt(2)
	v_mul_f32_e32 v179, v179, v195
	ds_write_b32 v234, v179 offset:7656
	s_waitcnt vmcnt(1)
	v_mul_f32_e32 v180, v180, v196
	ds_write_b32 v234, v180 offset:7920
	s_waitcnt vmcnt(0)
	v_mul_f32_e32 v181, v181, v197
	ds_write_b32 v234, v181 offset:8184
	s_mov_b32 s16, 0x100
	v_add_u32_e32 v0, 0x2100, v0
	s_waitcnt lgkmcnt(0)
	s_lshl_b32 s13, s8, 6
	s_cmpk_gt_i32 s8, 0x57
	s_mov_b64 s[16:17], -1
	s_cbranch_scc0 .LBB0_1218
	s_add_i32 s8, s13, 0x7fffea00
	s_and_b32 s8, s8, 0x7fffff00
	s_and_b32 s15, s14, 0x60
	s_or_b32 s8, s15, s8
	s_bitset1_b32 s8, 7
	s_mov_b64 s[16:17], 0

.LBB0_1448:
	s_and_b64 vcc, exec, s[8:9]
	s_cbranch_vccz .LBB0_1427
	s_ashr_i32 s8, s33, 31
	s_lshr_b32 s8, s8, 27
	s_add_i32 s8, s33, s8
	s_load_dwordx2 s[14:15], s[0:1], 0x68
	s_and_b32 s9, s8, 0x7ffffe0
	s_sub_i32 s9, s33, s9
	s_lshl_b32 s8, s8, 1
	s_and_b32 s12, s8, 0xffffffc0
	s_lshl_b32 s8, s9, 5
	s_ashr_i32 s9, s8, 31
	s_lshl_b64 s[16:17], s[8:9], 2
	s_waitcnt lgkmcnt(0)
	s_add_u32 s14, s14, s16
	s_addc_u32 s15, s15, s17
	v_mov_b32_e32 v11, v1
	v_lshl_add_u64 v[12:13], s[14:15], 0, v[10:11]
	v_or_b32_e32 v0, s12, v32
	s_mov_b32 s9, 0
	v_mov_b32_e32 v11, v38
	v_mov_b32_e32 v230, v0
	v_mov_b32_e32 v231, 0
	v_lshl_add_u64 v[232:233], v[230:231], 2, s[4:5]
	v_lshlrev_b64 v[230:231], 12, v[230:231]
	v_lshl_add_u64 v[230:231], v[12:13], 0, v[230:231]
	v_mov_b32_e32 v234, v11
	s_mov_b32 s58, 0x2000
	s_mov_b32 s59, 0
	global_load_dword v150, v[230:231], off nt
	v_lshl_add_u64 v[230:231], v[230:231], 0, s[58:59]
	global_load_dword v151, v[230:231], off nt
	v_lshl_add_u64 v[230:231], v[230:231], 0, s[58:59]
	global_load_dword v152, v[230:231], off nt
	v_lshl_add_u64 v[230:231], v[230:231], 0, s[58:59]
	global_load_dword v153, v[230:231], off nt
	v_lshl_add_u64 v[230:231], v[230:231], 0, s[58:59]
	global_load_dword v154, v[230:231], off nt
	v_lshl_add_u64 v[230:231], v[230:231], 0, s[58:59]
	global_load_dword v155, v[230:231], off nt
	v_lshl_add_u64 v[230:231], v[230:231], 0, s[58:59]
	global_load_dword v156, v[230:231], off nt
	v_lshl_add_u64 v[230:231], v[230:231], 0, s[58:59]
	global_load_dword v157, v[230:231], off nt
	v_lshl_add_u64 v[230:231], v[230:231], 0, s[58:59]
	global_load_dword v158, v[230:231], off nt
	v_lshl_add_u64 v[230:231], v[230:231], 0, s[58:59]
	global_load_dword v159, v[230:231], off nt
	v_lshl_add_u64 v[230:231], v[230:231], 0, s[58:59]
	global_load_dword v160, v[230:231], off nt
	v_lshl_add_u64 v[230:231], v[230:231], 0, s[58:59]
	global_load_dword v161, v[230:231], off nt
	v_lshl_add_u64 v[230:231], v[230:231], 0, s[58:59]
	global_load_dword v162, v[230:231], off nt
	v_lshl_add_u64 v[230:231], v[230:231], 0, s[58:59]
	global_load_dword v163, v[230:231], off nt
	v_lshl_add_u64 v[230:231], v[230:231], 0, s[58:59]
	global_load_dword v164, v[230:231], off nt
	v_lshl_add_u64 v[230:231], v[230:231], 0, s[58:59]
	global_load_dword v165, v[230:231], off nt
	v_lshl_add_u64 v[230:231], v[230:231], 0, s[58:59]
	global_load_dword v166, v[230:231], off nt
	v_lshl_add_u64 v[230:231], v[230:231], 0, s[58:59]
	global_load_dword v167, v[230:231], off nt
	v_lshl_add_u64 v[230:231], v[230:231], 0, s[58:59]
	global_load_dword v168, v[230:231], off nt
	v_lshl_add_u64 v[230:231], v[230:231], 0, s[58:59]
	global_load_dword v169, v[230:231], off nt
	v_lshl_add_u64 v[230:231], v[230:231], 0, s[58:59]
	global_load_dword v170, v[230:231], off nt
	v_lshl_add_u64 v[230:231], v[230:231], 0, s[58:59]
	global_load_dword v171, v[230:231], off nt
	v_lshl_add_u64 v[230:231], v[230:231], 0, s[58:59]
	global_load_dword v172, v[230:231], off nt
	v_lshl_add_u64 v[230:231], v[230:231], 0, s[58:59]
	global_load_dword v173, v[230:231], off nt
	v_lshl_add_u64 v[230:231], v[230:231], 0, s[58:59]
	global_load_dword v174, v[230:231], off nt
	v_lshl_add_u64 v[230:231], v[230:231], 0, s[58:59]
	global_load_dword v175, v[230:231], off nt
	v_lshl_add_u64 v[230:231], v[230:231], 0, s[58:59]
	global_load_dword v176, v[230:231], off nt
	v_lshl_add_u64 v[230:231], v[230:231], 0, s[58:59]
	global_load_dword v177, v[230:231], off nt
	v_lshl_add_u64 v[230:231], v[230:231], 0, s[58:59]
	global_load_dword v178, v[230:231], off nt
	v_lshl_add_u64 v[230:231], v[230:231], 0, s[58:59]
	global_load_dword v179, v[230:231], off nt
	v_lshl_add_u64 v[230:231], v[230:231], 0, s[58:59]
	global_load_dword v180, v[230:231], off nt
	v_lshl_add_u64 v[230:231], v[230:231], 0, s[58:59]
	global_load_dword v181, v[230:231], off nt
	global_load_dword v182, v[232:233], off
	global_load_dword v183, v[232:233], off offset:8
	global_load_dword v184, v[232:233], off offset:16
	global_load_dword v185, v[232:233], off offset:24
	global_load_dword v186, v[232:233], off offset:32
	global_load_dword v187, v[232:233], off offset:40
	global_load_dword v188, v[232:233], off offset:48
	global_load_dword v189, v[232:233], off offset:56
	global_load_dword v190, v[232:233], off offset:64
	global_load_dword v191, v[232:233], off offset:72
	global_load_dword v192, v[232:233], off offset:80
	global_load_dword v193, v[232:233], off offset:88
	global_load_dword v194, v[232:233], off offset:96
	global_load_dword v195, v[232:233], off offset:104
	global_load_dword v196, v[232:233], off offset:112
	global_load_dword v197, v[232:233], off offset:120
	s_waitcnt vmcnt(15)
	v_mul_f32_e32 v150, v150, v182
	ds_write_b32 v234, v150
	s_waitcnt vmcnt(14)
	v_mul_f32_e32 v151, v151, v183
	ds_write_b32 v234, v151 offset:264
	s_waitcnt vmcnt(13)
	v_mul_f32_e32 v152, v152, v184
	ds_write_b32 v234, v152 offset:528
	s_waitcnt vmcnt(12)
	v_mul_f32_e32 v153, v153, v185
	ds_write_b32 v234, v153 offset:792
	s_waitcnt vmcnt(11)
	v_mul_f32_e32 v154, v154, v186
	ds_write_b32 v234, v154 offset:1056
	s_waitcnt vmcnt(10)
	v_mul_f32_e32 v155, v155, v187
	ds_write_b32 v234, v155 offset:1320
	s_waitcnt vmcnt(9)
	v_mul_f32_e32 v156, v156, v188
	ds_write_b32 v234, v156 offset:1584
	s_waitcnt vmcnt(8)
	v_mul_f32_e32 v157, v157, v189
	ds_write_b32 v234, v157 offset:1848
	s_waitcnt vmcnt(7)
	v_mul_f32_e32 v158, v158, v190
	ds_write_b32 v234, v158 offset:2112
	s_waitcnt vmcnt(6)
	v_mul_f32_e32 v159, v159, v191
	ds_write_b32 v234, v159 offset:2376
	s_waitcnt vmcnt(5)
	v_mul_f32_e32 v160, v160, v192
	ds_write_b32 v234, v160 offset:2640
	s_waitcnt vmcnt(4)
	v_mul_f32_e32 v161, v161, v193
	ds_write_b32 v234, v161 offset:2904
	s_waitcnt vmcnt(3)
	v_mul_f32_e32 v162, v162, v194
	ds_write_b32 v234, v162 offset:3168
	s_waitcnt vmcnt(2)
	v_mul_f32_e32 v163, v163, v195
	ds_write_b32 v234, v163 offset:3432
	s_waitcnt vmcnt(1)
	v_mul_f32_e32 v164, v164, v196
	ds_write_b32 v234, v164 offset:3696
	s_waitcnt vmcnt(0)
	v_mul_f32_e32 v165, v165, v197
	ds_write_b32 v234, v165 offset:3960
	global_load_dword v182, v[232:233], off offset:128
	global_load_dword v183, v[232:233], off offset:136
	global_load_dword v184, v[232:233], off offset:144
	global_load_dword v185, v[232:233], off offset:152
	global_load_dword v186, v[232:233], off offset:160
	global_load_dword v187, v[232:233], off offset:168
	global_load_dword v188, v[232:233], off offset:176
	global_load_dword v189, v[232:233], off offset:184
	global_load_dword v190, v[232:233], off offset:192
	global_load_dword v191, v[232:233], off offset:200
	global_load_dword v192, v[232:233], off offset:208
	global_load_dword v193, v[232:233], off offset:216
	global_load_dword v194, v[232:233], off offset:224
	global_load_dword v195, v[232:233], off offset:232
	global_load_dword v196, v[232:233], off offset:240
	global_load_dword v197, v[232:233], off offset:248
	s_waitcnt vmcnt(15)
	v_mul_f32_e32 v166, v166, v182
	ds_write_b32 v234, v166 offset:4224
	s_waitcnt vmcnt(14)
	v_mul_f32_e32 v167, v167, v183
	ds_write_b32 v234, v167 offset:4488
	s_waitcnt vmcnt(13)
	v_mul_f32_e32 v168, v168, v184
	ds_write_b32 v234, v168 offset:4752
	s_waitcnt vmcnt(12)
	v_mul_f32_e32 v169, v169, v185
	ds_write_b32 v234, v169 offset:5016
	s_waitcnt vmcnt(11)
	v_mul_f32_e32 v170, v170, v186
	ds_write_b32 v234, v170 offset:5280
	s_waitcnt vmcnt(10)
	v_mul_f32_e32 v171, v171, v187
	ds_write_b32 v234, v171 offset:5544
	s_waitcnt vmcnt(9)
	v_mul_f32_e32 v172, v172, v188
	ds_write_b32 v234, v172 offset:5808
	s_waitcnt vmcnt(8)
	v_mul_f32_e32 v173, v173, v189
	ds_write_b32 v234, v173 offset:6072
	s_waitcnt vmcnt(7)
	v_mul_f32_e32 v174, v174, v190
	ds_write_b32 v234, v174 offset:6336
	s_waitcnt vmcnt(6)
	v_mul_f32_e32 v175, v175, v191
	ds_write_b32 v234, v175 offset:6600
	s_waitcnt vmcnt(5)
	v_mul_f32_e32 v176, v176, v192
	ds_write_b32 v234, v176 offset:6864
	s_waitcnt vmcnt(4)
	v_mul_f32_e32 v177, v177, v193
	ds_write_b32 v234, v177 offset:7128
	s_waitcnt vmcnt(3)
	v_mul_f32_e32 v178, v178, v194
	ds_write_b32 v234, v178 offset:7392
	s_waitcnt vmcnt(2)
	v_mul_f32_e32 v179, v179, v195
	ds_write_b32 v234, v179 offset:7656
	s_waitcnt vmcnt(1)
	v_mul_f32_e32 v180, v180, v196
	ds_write_b32 v234, v180 offset:7920
	s_waitcnt vmcnt(0)
	v_mul_f32_e32 v181, v181, v197
	ds_write_b32 v234, v181 offset:8184
	s_mov_b32 s9, 0x40
	v_add_u32_e32 v11, 0x2100, v11
	s_waitcnt lgkmcnt(0)
	ds_read2_b32 v[16:17], v34 offset0:33 offset1:41
	ds_read2_b32 v[18:19], v34 offset1:8
	ds_read2_b32 v[20:21], v34 offset0:66 offset1:74
	ds_read2_b32 v[22:23], v34 offset0:99 offset1:107
	ds_read2_b32 v[24:25], v34 offset0:132 offset1:140
	ds_read2_b32 v[26:27], v34 offset0:165 offset1:173
	ds_read2_b32 v[28:29], v34 offset0:198 offset1:206
	ds_read2_b32 v[30:31], v34 offset0:231 offset1:239
	v_or_b32_e32 v48, s8, v33
	s_ashr_i32 s13, s12, 31
	v_ashrrev_i32_e32 v49, 31, v48
	v_lshl_add_u64 v[46:47], s[12:13], 1, v[4:5]
	v_lshlrev_b64 v[48:49], 11, v[48:49]
	s_waitcnt lgkmcnt(6)
	v_cvt_pk_bf16_f32 v12, v18, v16
	s_waitcnt lgkmcnt(4)
	v_cvt_pk_bf16_f32 v13, v20, v22
	s_waitcnt lgkmcnt(2)
	v_cvt_pk_bf16_f32 v14, v24, v26
	s_waitcnt lgkmcnt(0)
	v_cvt_pk_bf16_f32 v15, v28, v30
	v_lshl_add_u64 v[48:49], v[46:47], 0, v[48:49]
	v_or_b32_e32 v16, s8, v35
	global_store_dwordx4 v[48:49], v[12:15], off
	s_nop 1
	v_cvt_pk_bf16_f32 v12, v19, v17
	v_ashrrev_i32_e32 v17, 31, v16
	v_cvt_pk_bf16_f32 v13, v21, v23
	v_cvt_pk_bf16_f32 v14, v25, v27
	v_cvt_pk_bf16_f32 v15, v29, v31
	v_lshlrev_b64 v[16:17], 11, v[16:17]
	ds_read2_b32 v[18:19], v34 offset0:49 offset1:57
	ds_read2_b32 v[20:21], v34 offset0:16 offset1:24
	ds_read2_b32 v[22:23], v34 offset0:82 offset1:90
	ds_read2_b32 v[24:25], v34 offset0:115 offset1:123
	ds_read2_b32 v[26:27], v34 offset0:148 offset1:156
	ds_read2_b32 v[28:29], v34 offset0:181 offset1:189
	ds_read2_b32 v[30:31], v34 offset0:214 offset1:222
	ds_read2_b32 v[48:49], v34 offset0:247 offset1:255
	v_lshl_add_u64 v[16:17], v[46:47], 0, v[16:17]
	global_store_dwordx4 v[16:17], v[12:15], off
	v_or_b32_e32 v16, s8, v36
	v_ashrrev_i32_e32 v17, 31, v16
	v_lshlrev_b64 v[16:17], 11, v[16:17]
	s_waitcnt lgkmcnt(6)
	v_cvt_pk_bf16_f32 v12, v20, v18
	s_waitcnt lgkmcnt(4)
	v_cvt_pk_bf16_f32 v13, v22, v24
	s_waitcnt lgkmcnt(2)
	v_cvt_pk_bf16_f32 v14, v26, v28
	s_waitcnt lgkmcnt(0)
	v_cvt_pk_bf16_f32 v15, v30, v48
	v_lshl_add_u64 v[16:17], v[46:47], 0, v[16:17]
	global_store_dwordx4 v[16:17], v[12:15], off
	v_or_b32_e32 v16, s8, v37
	v_ashrrev_i32_e32 v17, 31, v16
	v_lshlrev_b64 v[16:17], 11, v[16:17]
	v_cvt_pk_bf16_f32 v12, v21, v19
	v_cvt_pk_bf16_f32 v13, v23, v25
	v_cvt_pk_bf16_f32 v14, v27, v29
	v_cvt_pk_bf16_f32 v15, v31, v49
	v_lshl_add_u64 v[16:17], v[46:47], 0, v[16:17]
	global_store_dwordx4 v[16:17], v[12:15], off
	s_waitcnt lgkmcnt(0)
	s_branch .LBB0_1427

.LBB0_1737:
	s_ashr_i32 s1, s0, 31
	s_lshr_b32 s1, s1, 27
	s_add_i32 s1, s0, s1
	s_and_b32 s4, s1, 0x7ffffe0
	s_sub_i32 s4, s0, s4
	s_lshl_b32 s1, s1, 1
	s_lshl_b32 s4, s4, 5
	s_and_b32 s8, s1, 0xffffffc0
	s_ashr_i32 s5, s4, 31
	v_lshl_add_u64 v[4:5], s[4:5], 2, v[0:1]
	v_or_b32_e32 v13, s8, v6
	v_mov_b32_e32 v14, v12
	s_mov_b32 s1, 0
	v_mov_b32_e32 v230, v13
	v_mov_b32_e32 v231, 0
	v_lshlrev_b64 v[230:231], 12, v[230:231]
	v_lshl_add_u64 v[230:231], v[4:5], 0, v[230:231]
	v_mov_b32_e32 v234, v14
	s_mov_b32 s52, 0x2000
	s_mov_b32 s53, 0
	global_load_dword v150, v[230:231], off nt
	v_lshl_add_u64 v[230:231], v[230:231], 0, s[52:53]
	global_load_dword v151, v[230:231], off nt
	v_lshl_add_u64 v[230:231], v[230:231], 0, s[52:53]
	global_load_dword v152, v[230:231], off nt
	v_lshl_add_u64 v[230:231], v[230:231], 0, s[52:53]
	global_load_dword v153, v[230:231], off nt
	v_lshl_add_u64 v[230:231], v[230:231], 0, s[52:53]
	global_load_dword v154, v[230:231], off nt
	v_lshl_add_u64 v[230:231], v[230:231], 0, s[52:53]
	global_load_dword v155, v[230:231], off nt
	v_lshl_add_u64 v[230:231], v[230:231], 0, s[52:53]
	global_load_dword v156, v[230:231], off nt
	v_lshl_add_u64 v[230:231], v[230:231], 0, s[52:53]
	global_load_dword v157, v[230:231], off nt
	v_lshl_add_u64 v[230:231], v[230:231], 0, s[52:53]
	global_load_dword v158, v[230:231], off nt
	v_lshl_add_u64 v[230:231], v[230:231], 0, s[52:53]
	global_load_dword v159, v[230:231], off nt
	v_lshl_add_u64 v[230:231], v[230:231], 0, s[52:53]
	global_load_dword v160, v[230:231], off nt
	v_lshl_add_u64 v[230:231], v[230:231], 0, s[52:53]
	global_load_dword v161, v[230:231], off nt
	v_lshl_add_u64 v[230:231], v[230:231], 0, s[52:53]
	global_load_dword v162, v[230:231], off nt
	v_lshl_add_u64 v[230:231], v[230:231], 0, s[52:53]
	global_load_dword v163, v[230:231], off nt
	v_lshl_add_u64 v[230:231], v[230:231], 0, s[52:53]
	global_load_dword v164, v[230:231], off nt
	v_lshl_add_u64 v[230:231], v[230:231], 0, s[52:53]
	global_load_dword v165, v[230:231], off nt
	v_lshl_add_u64 v[230:231], v[230:231], 0, s[52:53]
	global_load_dword v166, v[230:231], off nt
	v_lshl_add_u64 v[230:231], v[230:231], 0, s[52:53]
	global_load_dword v167, v[230:231], off nt
	v_lshl_add_u64 v[230:231], v[230:231], 0, s[52:53]
	global_load_dword v168, v[230:231], off nt
	v_lshl_add_u64 v[230:231], v[230:231], 0, s[52:53]
	global_load_dword v169, v[230:231], off nt
	v_lshl_add_u64 v[230:231], v[230:231], 0, s[52:53]
	global_load_dword v170, v[230:231], off nt
	v_lshl_add_u64 v[230:231], v[230:231], 0, s[52:53]
	global_load_dword v171, v[230:231], off nt
	v_lshl_add_u64 v[230:231], v[230:231], 0, s[52:53]
	global_load_dword v172, v[230:231], off nt
	v_lshl_add_u64 v[230:231], v[230:231], 0, s[52:53]
	global_load_dword v173, v[230:231], off nt
	v_lshl_add_u64 v[230:231], v[230:231], 0, s[52:53]
	global_load_dword v174, v[230:231], off nt
	v_lshl_add_u64 v[230:231], v[230:231], 0, s[52:53]
	global_load_dword v175, v[230:231], off nt
	v_lshl_add_u64 v[230:231], v[230:231], 0, s[52:53]
	global_load_dword v176, v[230:231], off nt
	v_lshl_add_u64 v[230:231], v[230:231], 0, s[52:53]
	global_load_dword v177, v[230:231], off nt
	v_lshl_add_u64 v[230:231], v[230:231], 0, s[52:53]
	global_load_dword v178, v[230:231], off nt
	v_lshl_add_u64 v[230:231], v[230:231], 0, s[52:53]
	global_load_dword v179, v[230:231], off nt
	v_lshl_add_u64 v[230:231], v[230:231], 0, s[52:53]
	global_load_dword v180, v[230:231], off nt
	v_lshl_add_u64 v[230:231], v[230:231], 0, s[52:53]
	global_load_dword v181, v[230:231], off nt
	s_waitcnt vmcnt(31)
	ds_write_b32 v234, v150
	s_waitcnt vmcnt(30)
	ds_write_b32 v234, v151 offset:264
	s_waitcnt vmcnt(29)
	ds_write_b32 v234, v152 offset:528
	s_waitcnt vmcnt(28)
	ds_write_b32 v234, v153 offset:792
	s_waitcnt vmcnt(27)
	ds_write_b32 v234, v154 offset:1056
	s_waitcnt vmcnt(26)
	ds_write_b32 v234, v155 offset:1320
	s_waitcnt vmcnt(25)
	ds_write_b32 v234, v156 offset:1584
	s_waitcnt vmcnt(24)
	ds_write_b32 v234, v157 offset:1848
	s_waitcnt vmcnt(23)
	ds_write_b32 v234, v158 offset:2112
	s_waitcnt vmcnt(22)
	ds_write_b32 v234, v159 offset:2376
	s_waitcnt vmcnt(21)
	ds_write_b32 v234, v160 offset:2640
	s_waitcnt vmcnt(20)
	ds_write_b32 v234, v161 offset:2904
	s_waitcnt vmcnt(19)
	ds_write_b32 v234, v162 offset:3168
	s_waitcnt vmcnt(18)
	ds_write_b32 v234, v163 offset:3432
	s_waitcnt vmcnt(17)
	ds_write_b32 v234, v164 offset:3696
	s_waitcnt vmcnt(16)
	ds_write_b32 v234, v165 offset:3960
	s_waitcnt vmcnt(15)
	ds_write_b32 v234, v166 offset:4224
	s_waitcnt vmcnt(14)
	ds_write_b32 v234, v167 offset:4488
	s_waitcnt vmcnt(13)
	ds_write_b32 v234, v168 offset:4752
	s_waitcnt vmcnt(12)
	ds_write_b32 v234, v169 offset:5016
	s_waitcnt vmcnt(11)
	ds_write_b32 v234, v170 offset:5280
	s_waitcnt vmcnt(10)
	ds_write_b32 v234, v171 offset:5544
	s_waitcnt vmcnt(9)
	ds_write_b32 v234, v172 offset:5808
	s_waitcnt vmcnt(8)
	ds_write_b32 v234, v173 offset:6072
	s_waitcnt vmcnt(7)
	ds_write_b32 v234, v174 offset:6336
	s_waitcnt vmcnt(6)
	ds_write_b32 v234, v175 offset:6600
	s_waitcnt vmcnt(5)
	ds_write_b32 v234, v176 offset:6864
	s_waitcnt vmcnt(4)
	ds_write_b32 v234, v177 offset:7128
	s_waitcnt vmcnt(3)
	ds_write_b32 v234, v178 offset:7392
	s_waitcnt vmcnt(2)
	ds_write_b32 v234, v179 offset:7656
	s_waitcnt vmcnt(1)
	ds_write_b32 v234, v180 offset:7920
	s_waitcnt vmcnt(0)
	ds_write_b32 v234, v181 offset:8184
	s_mov_b32 s1, 0x40
	v_add_u32_e32 v14, 0x2100, v14
	s_waitcnt lgkmcnt(0)
	ds_read2_b32 v[4:5], v8 offset0:33 offset1:41
	ds_read2_b32 v[18:19], v8 offset1:8
	ds_read2_b32 v[20:21], v8 offset0:66 offset1:74
	ds_read2_b32 v[22:23], v8 offset0:99 offset1:107
	ds_read2_b32 v[24:25], v8 offset0:132 offset1:140
	ds_read2_b32 v[26:27], v8 offset0:165 offset1:173
	ds_read2_b32 v[28:29], v8 offset0:198 offset1:206
	ds_read2_b32 v[30:31], v8 offset0:231 offset1:239
	v_or_b32_e32 v34, s4, v7
	s_ashr_i32 s9, s8, 31
	v_ashrrev_i32_e32 v35, 31, v34
	v_lshl_add_u64 v[32:33], s[8:9], 1, v[2:3]
	v_lshlrev_b64 v[34:35], 11, v[34:35]
	s_waitcnt lgkmcnt(6)
	v_cvt_pk_bf16_f32 v14, v18, v4
	s_waitcnt lgkmcnt(4)
	v_cvt_pk_bf16_f32 v15, v20, v22
	s_waitcnt lgkmcnt(2)
	v_cvt_pk_bf16_f32 v16, v24, v26
	s_waitcnt lgkmcnt(0)
	v_cvt_pk_bf16_f32 v17, v28, v30
	v_lshl_add_u64 v[34:35], v[32:33], 0, v[34:35]
	v_or_b32_e32 v4, s4, v9
	global_store_dwordx4 v[34:35], v[14:17], off
	s_add_i32 s0, s0, s96
	s_cmpk_lt_i32 s0, 0x200
	v_cvt_pk_bf16_f32 v14, v19, v5
	v_ashrrev_i32_e32 v5, 31, v4
	v_cvt_pk_bf16_f32 v15, v21, v23
	v_cvt_pk_bf16_f32 v16, v25, v27
	v_cvt_pk_bf16_f32 v17, v29, v31
	v_lshlrev_b64 v[4:5], 11, v[4:5]
	ds_read2_b32 v[18:19], v8 offset0:49 offset1:57
	ds_read2_b32 v[20:21], v8 offset0:16 offset1:24
	ds_read2_b32 v[22:23], v8 offset0:82 offset1:90
	ds_read2_b32 v[24:25], v8 offset0:115 offset1:123
	ds_read2_b32 v[26:27], v8 offset0:148 offset1:156
	ds_read2_b32 v[28:29], v8 offset0:181 offset1:189
	ds_read2_b32 v[30:31], v8 offset0:214 offset1:222
	ds_read2_b32 v[34:35], v8 offset0:247 offset1:255
	v_lshl_add_u64 v[4:5], v[32:33], 0, v[4:5]
	global_store_dwordx4 v[4:5], v[14:17], off
	v_or_b32_e32 v4, s4, v10
	v_ashrrev_i32_e32 v5, 31, v4
	v_lshlrev_b64 v[4:5], 11, v[4:5]
	s_waitcnt lgkmcnt(6)
	v_cvt_pk_bf16_f32 v14, v20, v18
	s_waitcnt lgkmcnt(4)
	v_cvt_pk_bf16_f32 v15, v22, v24
	s_waitcnt lgkmcnt(2)
	v_cvt_pk_bf16_f32 v16, v26, v28
	s_waitcnt lgkmcnt(0)
	v_cvt_pk_bf16_f32 v17, v30, v34
	v_lshl_add_u64 v[4:5], v[32:33], 0, v[4:5]
	global_store_dwordx4 v[4:5], v[14:17], off
	v_or_b32_e32 v4, s4, v11
	v_ashrrev_i32_e32 v5, 31, v4
	v_lshlrev_b64 v[4:5], 11, v[4:5]
	v_cvt_pk_bf16_f32 v14, v21, v19
	v_cvt_pk_bf16_f32 v15, v23, v25
	v_cvt_pk_bf16_f32 v16, v27, v29
	v_cvt_pk_bf16_f32 v17, v31, v35
	v_lshl_add_u64 v[4:5], v[32:33], 0, v[4:5]
	global_store_dwordx4 v[4:5], v[14:17], off
	s_waitcnt lgkmcnt(0)
	s_cbranch_scc1 .LBB0_1737

.LBB0_1881:
	s_and_b64 vcc, exec, s[12:13]
	s_cbranch_vccz .LBB0_1876
	s_mul_hi_i32 s8, s33, 0x2e8ba2e9
	s_lshr_b32 s12, s8, 31
	s_ashr_i32 s8, s8, 5
	s_add_i32 s12, s8, s12
	s_load_dwordx2 s[16:17], s[0:1], 0x18
	s_mul_i32 s8, s12, 0xb0
	s_sub_i32 s8, s33, s8
	s_lshl_b32 s14, s8, 5
	s_ashr_i32 s15, s14, 31
	s_lshl_b32 s12, s12, 6
	s_lshl_b64 s[24:25], s[14:15], 2
	s_waitcnt lgkmcnt(0)
	s_add_u32 s13, s16, s24
	s_addc_u32 s15, s17, s25
	s_add_u32 s16, s13, 0x4200000
	v_or_b32_e32 v12, s12, v49
	s_addc_u32 s17, s15, 0
	v_or_b32_e32 v16, s12, v50
	v_or_b32_e32 v20, s12, v51
	v_or_b32_e32 v24, s12, v52
	v_or_b32_e32 v28, s12, v53
	v_or_b32_e32 v32, s12, v54
	v_or_b32_e32 v36, s12, v55
	v_ashrrev_i32_e32 v13, 31, v12
	v_mov_b64_e32 v[40:41], s[16:17]
	v_ashrrev_i32_e32 v17, 31, v16
	v_ashrrev_i32_e32 v21, 31, v20
	v_ashrrev_i32_e32 v25, 31, v24
	v_ashrrev_i32_e32 v29, 31, v28
	v_ashrrev_i32_e32 v33, 31, v32
	v_ashrrev_i32_e32 v37, 31, v36
	v_or_b32_e32 v56, s12, v42
	v_lshl_add_u64 v[10:11], v[12:13], 2, s[4:5]
	v_mad_i64_i32 v[12:13], s[16:17], v12, s22, v[40:41]
	v_lshl_add_u64 v[14:15], v[16:17], 2, s[4:5]
	v_mad_i64_i32 v[16:17], s[16:17], v16, s22, v[40:41]
	v_lshl_add_u64 v[18:19], v[20:21], 2, s[4:5]
	v_mad_i64_i32 v[20:21], s[16:17], v20, s22, v[40:41]
	v_lshl_add_u64 v[22:23], v[24:25], 2, s[4:5]
	v_mad_i64_i32 v[24:25], s[16:17], v24, s22, v[40:41]
	v_lshl_add_u64 v[26:27], v[28:29], 2, s[4:5]
	v_mad_i64_i32 v[28:29], s[16:17], v28, s22, v[40:41]
	v_lshl_add_u64 v[30:31], v[32:33], 2, s[4:5]
	v_mad_i64_i32 v[32:33], s[16:17], v32, s22, v[40:41]
	v_lshl_add_u64 v[34:35], v[36:37], 2, s[4:5]
	v_mad_i64_i32 v[36:37], s[16:17], v36, s22, v[40:41]
	v_ashrrev_i32_e32 v57, 31, v56
	v_mad_i64_i32 v[40:41], s[16:17], v56, s22, v[40:41]
	v_lshl_add_u64 v[38:39], v[56:57], 2, s[4:5]
	s_mov_b64 s[16:17], 0
	v_mov_b32_e32 v0, v48
	v_lshl_add_u64 v[230:231], v[40:41], 0, v[6:7]
	v_mov_b32_e32 v232, v38
	v_mov_b32_e32 v233, v39
	v_mov_b32_e32 v234, v0
	s_mov_b32 s58, 0xb000
	s_mov_b32 s59, 0
	global_load_dword v150, v[230:231], off nt
	v_lshl_add_u64 v[230:231], v[230:231], 0, s[58:59]
	global_load_dword v151, v[230:231], off nt
	v_lshl_add_u64 v[230:231], v[230:231], 0, s[58:59]
	global_load_dword v152, v[230:231], off nt
	v_lshl_add_u64 v[230:231], v[230:231], 0, s[58:59]
	global_load_dword v153, v[230:231], off nt
	v_lshl_add_u64 v[230:231], v[230:231], 0, s[58:59]
	global_load_dword v154, v[230:231], off nt
	v_lshl_add_u64 v[230:231], v[230:231], 0, s[58:59]
	global_load_dword v155, v[230:231], off nt
	v_lshl_add_u64 v[230:231], v[230:231], 0, s[58:59]
	global_load_dword v156, v[230:231], off nt
	v_lshl_add_u64 v[230:231], v[230:231], 0, s[58:59]
	global_load_dword v157, v[230:231], off nt
	v_lshl_add_u64 v[230:231], v[230:231], 0, s[58:59]
	global_load_dword v158, v[230:231], off nt
	v_lshl_add_u64 v[230:231], v[230:231], 0, s[58:59]
	global_load_dword v159, v[230:231], off nt
	v_lshl_add_u64 v[230:231], v[230:231], 0, s[58:59]
	global_load_dword v160, v[230:231], off nt
	v_lshl_add_u64 v[230:231], v[230:231], 0, s[58:59]
	global_load_dword v161, v[230:231], off nt
	v_lshl_add_u64 v[230:231], v[230:231], 0, s[58:59]
	global_load_dword v162, v[230:231], off nt
	v_lshl_add_u64 v[230:231], v[230:231], 0, s[58:59]
	global_load_dword v163, v[230:231], off nt
	v_lshl_add_u64 v[230:231], v[230:231], 0, s[58:59]
	global_load_dword v164, v[230:231], off nt
	v_lshl_add_u64 v[230:231], v[230:231], 0, s[58:59]
	global_load_dword v165, v[230:231], off nt
	v_lshl_add_u64 v[230:231], v[230:231], 0, s[58:59]
	global_load_dword v166, v[230:231], off nt
	v_lshl_add_u64 v[230:231], v[230:231], 0, s[58:59]
	global_load_dword v167, v[230:231], off nt
	v_lshl_add_u64 v[230:231], v[230:231], 0, s[58:59]
	global_load_dword v168, v[230:231], off nt
	v_lshl_add_u64 v[230:231], v[230:231], 0, s[58:59]
	global_load_dword v169, v[230:231], off nt
	v_lshl_add_u64 v[230:231], v[230:231], 0, s[58:59]
	global_load_dword v170, v[230:231], off nt
	v_lshl_add_u64 v[230:231], v[230:231], 0, s[58:59]
	global_load_dword v171, v[230:231], off nt
	v_lshl_add_u64 v[230:231], v[230:231], 0, s[58:59]
	global_load_dword v172, v[230:231], off nt
	v_lshl_add_u64 v[230:231], v[230:231], 0, s[58:59]
	global_load_dword v173, v[230:231], off nt
	v_lshl_add_u64 v[230:231], v[230:231], 0, s[58:59]
	global_load_dword v174, v[230:231], off nt
	v_lshl_add_u64 v[230:231], v[230:231], 0, s[58:59]
	global_load_dword v175, v[230:231], off nt
	v_lshl_add_u64 v[230:231], v[230:231], 0, s[58:59]
	global_load_dword v176, v[230:231], off nt
	v_lshl_add_u64 v[230:231], v[230:231], 0, s[58:59]
	global_load_dword v177, v[230:231], off nt
	v_lshl_add_u64 v[230:231], v[230:231], 0, s[58:59]
	global_load_dword v178, v[230:231], off nt
	v_lshl_add_u64 v[230:231], v[230:231], 0, s[58:59]
	global_load_dword v179, v[230:231], off nt
	v_lshl_add_u64 v[230:231], v[230:231], 0, s[58:59]
	global_load_dword v180, v[230:231], off nt
	v_lshl_add_u64 v[230:231], v[230:231], 0, s[58:59]
	global_load_dword v181, v[230:231], off nt
	global_load_dword v182, v[232:233], off
	global_load_dword v183, v[232:233], off offset:8
	global_load_dword v184, v[232:233], off offset:16
	global_load_dword v185, v[232:233], off offset:24
	global_load_dword v186, v[232:233], off offset:32
	global_load_dword v187, v[232:233], off offset:40
	global_load_dword v188, v[232:233], off offset:48
	global_load_dword v189, v[232:233], off offset:56
	global_load_dword v190, v[232:233], off offset:64
	global_load_dword v191, v[232:233], off offset:72
	global_load_dword v192, v[232:233], off offset:80
	global_load_dword v193, v[232:233], off offset:88
	global_load_dword v194, v[232:233], off offset:96
	global_load_dword v195, v[232:233], off offset:104
	global_load_dword v196, v[232:233], off offset:112
	global_load_dword v197, v[232:233], off offset:120
	s_waitcnt vmcnt(15)
	v_mul_f32_e32 v150, v150, v182
	ds_write_b32 v234, v150
	s_waitcnt vmcnt(14)
	v_mul_f32_e32 v151, v151, v183
	ds_write_b32 v234, v151 offset:264
	s_waitcnt vmcnt(13)
	v_mul_f32_e32 v152, v152, v184
	ds_write_b32 v234, v152 offset:528
	s_waitcnt vmcnt(12)
	v_mul_f32_e32 v153, v153, v185
	ds_write_b32 v234, v153 offset:792
	s_waitcnt vmcnt(11)
	v_mul_f32_e32 v154, v154, v186
	ds_write_b32 v234, v154 offset:1056
	s_waitcnt vmcnt(10)
	v_mul_f32_e32 v155, v155, v187
	ds_write_b32 v234, v155 offset:1320
	s_waitcnt vmcnt(9)
	v_mul_f32_e32 v156, v156, v188
	ds_write_b32 v234, v156 offset:1584
	s_waitcnt vmcnt(8)
	v_mul_f32_e32 v157, v157, v189
	ds_write_b32 v234, v157 offset:1848
	s_waitcnt vmcnt(7)
	v_mul_f32_e32 v158, v158, v190
	ds_write_b32 v234, v158 offset:2112
	s_waitcnt vmcnt(6)
	v_mul_f32_e32 v159, v159, v191
	ds_write_b32 v234, v159 offset:2376
	s_waitcnt vmcnt(5)
	v_mul_f32_e32 v160, v160, v192
	ds_write_b32 v234, v160 offset:2640
	s_waitcnt vmcnt(4)
	v_mul_f32_e32 v161, v161, v193
	ds_write_b32 v234, v161 offset:2904
	s_waitcnt vmcnt(3)
	v_mul_f32_e32 v162, v162, v194
	ds_write_b32 v234, v162 offset:3168
	s_waitcnt vmcnt(2)
	v_mul_f32_e32 v163, v163, v195
	ds_write_b32 v234, v163 offset:3432
	s_waitcnt vmcnt(1)
	v_mul_f32_e32 v164, v164, v196
	ds_write_b32 v234, v164 offset:3696
	s_waitcnt vmcnt(0)
	v_mul_f32_e32 v165, v165, v197
	ds_write_b32 v234, v165 offset:3960
	global_load_dword v182, v[232:233], off offset:128
	global_load_dword v183, v[232:233], off offset:136
	global_load_dword v184, v[232:233], off offset:144
	global_load_dword v185, v[232:233], off offset:152
	global_load_dword v186, v[232:233], off offset:160
	global_load_dword v187, v[232:233], off offset:168
	global_load_dword v188, v[232:233], off offset:176
	global_load_dword v189, v[232:233], off offset:184
	global_load_dword v190, v[232:233], off offset:192
	global_load_dword v191, v[232:233], off offset:200
	global_load_dword v192, v[232:233], off offset:208
	global_load_dword v193, v[232:233], off offset:216
	global_load_dword v194, v[232:233], off offset:224
	global_load_dword v195, v[232:233], off offset:232
	global_load_dword v196, v[232:233], off offset:240
	global_load_dword v197, v[232:233], off offset:248
	s_waitcnt vmcnt(15)
	v_mul_f32_e32 v166, v166, v182
	ds_write_b32 v234, v166 offset:4224
	s_waitcnt vmcnt(14)
	v_mul_f32_e32 v167, v167, v183
	ds_write_b32 v234, v167 offset:4488
	s_waitcnt vmcnt(13)
	v_mul_f32_e32 v168, v168, v184
	ds_write_b32 v234, v168 offset:4752
	s_waitcnt vmcnt(12)
	v_mul_f32_e32 v169, v169, v185
	ds_write_b32 v234, v169 offset:5016
	s_waitcnt vmcnt(11)
	v_mul_f32_e32 v170, v170, v186
	ds_write_b32 v234, v170 offset:5280
	s_waitcnt vmcnt(10)
	v_mul_f32_e32 v171, v171, v187
	ds_write_b32 v234, v171 offset:5544
	s_waitcnt vmcnt(9)
	v_mul_f32_e32 v172, v172, v188
	ds_write_b32 v234, v172 offset:5808
	s_waitcnt vmcnt(8)
	v_mul_f32_e32 v173, v173, v189
	ds_write_b32 v234, v173 offset:6072
	s_waitcnt vmcnt(7)
	v_mul_f32_e32 v174, v174, v190
	ds_write_b32 v234, v174 offset:6336
	s_waitcnt vmcnt(6)
	v_mul_f32_e32 v175, v175, v191
	ds_write_b32 v234, v175 offset:6600
	s_waitcnt vmcnt(5)
	v_mul_f32_e32 v176, v176, v192
	ds_write_b32 v234, v176 offset:6864
	s_waitcnt vmcnt(4)
	v_mul_f32_e32 v177, v177, v193
	ds_write_b32 v234, v177 offset:7128
	s_waitcnt vmcnt(3)
	v_mul_f32_e32 v178, v178, v194
	ds_write_b32 v234, v178 offset:7392
	s_waitcnt vmcnt(2)
	v_mul_f32_e32 v179, v179, v195
	ds_write_b32 v234, v179 offset:7656
	s_waitcnt vmcnt(1)
	v_mul_f32_e32 v180, v180, v196
	ds_write_b32 v234, v180 offset:7920
	s_waitcnt vmcnt(0)
	v_mul_f32_e32 v181, v181, v197
	ds_write_b32 v234, v181 offset:8184
	s_mov_b32 s16, 0x100
	v_add_u32_e32 v0, 0x2100, v0
	s_waitcnt lgkmcnt(0)
	s_lshl_b32 s13, s8, 6
	s_cmpk_gt_i32 s8, 0x57
	s_mov_b64 s[16:17], -1
	s_cbranch_scc0 .LBB0_1886
	s_add_i32 s8, s13, 0x7fffea00
	s_and_b32 s8, s8, 0x7fffff00
	s_and_b32 s15, s14, 0x60
	s_or_b32 s8, s15, s8
	s_bitset1_b32 s8, 7
	s_mov_b64 s[16:17], 0

.LBB0_2096:
	s_cmpk_gt_i32 s33, 0x1ff
	s_mov_b64 s[12:13], -1
	s_cbranch_scc0 .LBB0_2100
	s_load_dwordx2 s[12:13], s[0:1], 0x28
	s_lshl_b32 s8, s16, 2
	s_and_b32 s14, s18, 0x1c0
	s_and_b32 s8, s8, 0xf80
	v_or_b32_e32 v8, s14, v31
	v_or_b32_e32 v10, s14, v32
	v_or_b32_e32 v12, s14, v33
	v_or_b32_e32 v14, s14, v34
	v_or_b32_e32 v16, s14, v35
	v_or_b32_e32 v18, s14, v36
	v_or_b32_e32 v20, s14, v37
	v_or_b32_e32 v22, s14, v24
	v_lshl_or_b32 v8, v8, 12, s8
	v_mov_b32_e32 v9, v1
	v_lshl_or_b32 v10, v10, 12, s8
	v_mov_b32_e32 v11, v1
	v_lshl_or_b32 v12, v12, 12, s8
	v_mov_b32_e32 v13, v1
	v_lshl_or_b32 v14, v14, 12, s8
	v_mov_b32_e32 v15, v1
	v_lshl_or_b32 v16, v16, 12, s8
	v_mov_b32_e32 v17, v1
	v_lshl_or_b32 v18, v18, 12, s8
	v_mov_b32_e32 v19, v1
	v_lshl_or_b32 v20, v20, 12, s8
	v_mov_b32_e32 v21, v1
	v_lshl_or_b32 v22, v22, 12, s8
	v_mov_b32_e32 v23, v1
	s_waitcnt lgkmcnt(0)
	v_lshl_add_u64 v[38:39], s[12:13], 0, v[6:7]
	v_lshl_add_u64 v[8:9], v[38:39], 0, v[8:9]
	v_lshl_add_u64 v[10:11], v[38:39], 0, v[10:11]
	v_lshl_add_u64 v[12:13], v[38:39], 0, v[12:13]
	v_lshl_add_u64 v[14:15], v[38:39], 0, v[14:15]
	v_lshl_add_u64 v[16:17], v[38:39], 0, v[16:17]
	v_lshl_add_u64 v[18:19], v[38:39], 0, v[18:19]
	v_lshl_add_u64 v[20:21], v[38:39], 0, v[20:21]
	v_lshl_add_u64 v[22:23], v[38:39], 0, v[22:23]
	s_mov_b64 s[12:13], 0
	v_mov_b32_e32 v38, v30
	v_mov_b32_e32 v230, v22
	v_mov_b32_e32 v231, v23
	v_mov_b32_e32 v234, v38
	s_mov_b32 s62, 0x2000
	s_mov_b32 s63, 0
	global_load_dword v150, v[230:231], off nt
	v_lshl_add_u64 v[230:231], v[230:231], 0, s[62:63]
	global_load_dword v151, v[230:231], off nt
	v_lshl_add_u64 v[230:231], v[230:231], 0, s[62:63]
	global_load_dword v152, v[230:231], off nt
	v_lshl_add_u64 v[230:231], v[230:231], 0, s[62:63]
	global_load_dword v153, v[230:231], off nt
	v_lshl_add_u64 v[230:231], v[230:231], 0, s[62:63]
	global_load_dword v154, v[230:231], off nt
	v_lshl_add_u64 v[230:231], v[230:231], 0, s[62:63]
	global_load_dword v155, v[230:231], off nt
	v_lshl_add_u64 v[230:231], v[230:231], 0, s[62:63]
	global_load_dword v156, v[230:231], off nt
	v_lshl_add_u64 v[230:231], v[230:231], 0, s[62:63]
	global_load_dword v157, v[230:231], off nt
	v_lshl_add_u64 v[230:231], v[230:231], 0, s[62:63]
	global_load_dword v158, v[230:231], off nt
	v_lshl_add_u64 v[230:231], v[230:231], 0, s[62:63]
	global_load_dword v159, v[230:231], off nt
	v_lshl_add_u64 v[230:231], v[230:231], 0, s[62:63]
	global_load_dword v160, v[230:231], off nt
	v_lshl_add_u64 v[230:231], v[230:231], 0, s[62:63]
	global_load_dword v161, v[230:231], off nt
	v_lshl_add_u64 v[230:231], v[230:231], 0, s[62:63]
	global_load_dword v162, v[230:231], off nt
	v_lshl_add_u64 v[230:231], v[230:231], 0, s[62:63]
	global_load_dword v163, v[230:231], off nt
	v_lshl_add_u64 v[230:231], v[230:231], 0, s[62:63]
	global_load_dword v164, v[230:231], off nt
	v_lshl_add_u64 v[230:231], v[230:231], 0, s[62:63]
	global_load_dword v165, v[230:231], off nt
	v_lshl_add_u64 v[230:231], v[230:231], 0, s[62:63]
	global_load_dword v166, v[230:231], off nt
	v_lshl_add_u64 v[230:231], v[230:231], 0, s[62:63]
	global_load_dword v167, v[230:231], off nt
	v_lshl_add_u64 v[230:231], v[230:231], 0, s[62:63]
	global_load_dword v168, v[230:231], off nt
	v_lshl_add_u64 v[230:231], v[230:231], 0, s[62:63]
	global_load_dword v169, v[230:231], off nt
	v_lshl_add_u64 v[230:231], v[230:231], 0, s[62:63]
	global_load_dword v170, v[230:231], off nt
	v_lshl_add_u64 v[230:231], v[230:231], 0, s[62:63]
	global_load_dword v171, v[230:231], off nt
	v_lshl_add_u64 v[230:231], v[230:231], 0, s[62:63]
	global_load_dword v172, v[230:231], off nt
	v_lshl_add_u64 v[230:231], v[230:231], 0, s[62:63]
	global_load_dword v173, v[230:231], off nt
	v_lshl_add_u64 v[230:231], v[230:231], 0, s[62:63]
	global_load_dword v174, v[230:231], off nt
	v_lshl_add_u64 v[230:231], v[230:231], 0, s[62:63]
	global_load_dword v175, v[230:231], off nt
	v_lshl_add_u64 v[230:231], v[230:231], 0, s[62:63]
	global_load_dword v176, v[230:231], off nt
	v_lshl_add_u64 v[230:231], v[230:231], 0, s[62:63]
	global_load_dword v177, v[230:231], off nt
	v_lshl_add_u64 v[230:231], v[230:231], 0, s[62:63]
	global_load_dword v178, v[230:231], off nt
	v_lshl_add_u64 v[230:231], v[230:231], 0, s[62:63]
	global_load_dword v179, v[230:231], off nt
	v_lshl_add_u64 v[230:231], v[230:231], 0, s[62:63]
	global_load_dword v180, v[230:231], off nt
	v_lshl_add_u64 v[230:231], v[230:231], 0, s[62:63]
	global_load_dword v181, v[230:231], off nt
	s_waitcnt vmcnt(31)
	ds_write_b32 v234, v150
	s_waitcnt vmcnt(30)
	ds_write_b32 v234, v151 offset:264
	s_waitcnt vmcnt(29)
	ds_write_b32 v234, v152 offset:528
	s_waitcnt vmcnt(28)
	ds_write_b32 v234, v153 offset:792
	s_waitcnt vmcnt(27)
	ds_write_b32 v234, v154 offset:1056
	s_waitcnt vmcnt(26)
	ds_write_b32 v234, v155 offset:1320
	s_waitcnt vmcnt(25)
	ds_write_b32 v234, v156 offset:1584
	s_waitcnt vmcnt(24)
	ds_write_b32 v234, v157 offset:1848
	s_waitcnt vmcnt(23)
	ds_write_b32 v234, v158 offset:2112
	s_waitcnt vmcnt(22)
	ds_write_b32 v234, v159 offset:2376
	s_waitcnt vmcnt(21)
	ds_write_b32 v234, v160 offset:2640
	s_waitcnt vmcnt(20)
	ds_write_b32 v234, v161 offset:2904
	s_waitcnt vmcnt(19)
	ds_write_b32 v234, v162 offset:3168
	s_waitcnt vmcnt(18)
	ds_write_b32 v234, v163 offset:3432
	s_waitcnt vmcnt(17)
	ds_write_b32 v234, v164 offset:3696
	s_waitcnt vmcnt(16)
	ds_write_b32 v234, v165 offset:3960
	s_waitcnt vmcnt(15)
	ds_write_b32 v234, v166 offset:4224
	s_waitcnt vmcnt(14)
	ds_write_b32 v234, v167 offset:4488
	s_waitcnt vmcnt(13)
	ds_write_b32 v234, v168 offset:4752
	s_waitcnt vmcnt(12)
	ds_write_b32 v234, v169 offset:5016
	s_waitcnt vmcnt(11)
	ds_write_b32 v234, v170 offset:5280
	s_waitcnt vmcnt(10)
	ds_write_b32 v234, v171 offset:5544
	s_waitcnt vmcnt(9)
	ds_write_b32 v234, v172 offset:5808
	s_waitcnt vmcnt(8)
	ds_write_b32 v234, v173 offset:6072
	s_waitcnt vmcnt(7)
	ds_write_b32 v234, v174 offset:6336
	s_waitcnt vmcnt(6)
	ds_write_b32 v234, v175 offset:6600
	s_waitcnt vmcnt(5)
	ds_write_b32 v234, v176 offset:6864
	s_waitcnt vmcnt(4)
	ds_write_b32 v234, v177 offset:7128
	s_waitcnt vmcnt(3)
	ds_write_b32 v234, v178 offset:7392
	s_waitcnt vmcnt(2)
	ds_write_b32 v234, v179 offset:7656
	s_waitcnt vmcnt(1)
	ds_write_b32 v234, v180 offset:7920
	s_waitcnt vmcnt(0)
	ds_write_b32 v234, v181 offset:8184
	s_mov_b32 s12, 0x40000
	v_add_u32_e32 v38, 0x2100, v38
	s_waitcnt lgkmcnt(0)
	ds_read2_b32 v[12:13], v26 offset0:33 offset1:41
	ds_read2_b32 v[14:15], v26 offset1:8
	ds_read2_b32 v[16:17], v26 offset0:66 offset1:74
	ds_read2_b32 v[18:19], v26 offset0:99 offset1:107
	ds_read2_b32 v[20:21], v26 offset0:132 offset1:140
	ds_read2_b32 v[22:23], v26 offset0:165 offset1:173
	ds_read2_b32 v[38:39], v26 offset0:198 offset1:206
	ds_read2_b32 v[40:41], v26 offset0:231 offset1:239
	s_lshl_b32 s8, s33, 5
	s_and_b32 s12, s8, 0x3e0
	s_lshl_b32 s8, s33, 2
	s_and_b32 s8, s8, 0x380
	s_waitcnt lgkmcnt(6)
	v_cvt_pk_bf16_f32 v8, v14, v12
	v_or_b32_e32 v12, s12, v25
	v_lshl_add_u64 v[42:43], v[2:3], 0, s[8:9]
	v_lshlrev_b32_e32 v44, 9, v12
	v_mov_b32_e32 v45, v1
	s_waitcnt lgkmcnt(4)
	v_cvt_pk_bf16_f32 v9, v16, v18
	s_waitcnt lgkmcnt(2)
	v_cvt_pk_bf16_f32 v10, v20, v22
	s_waitcnt lgkmcnt(0)
	v_cvt_pk_bf16_f32 v11, v38, v40
	v_lshl_add_u64 v[44:45], v[42:43], 0, v[44:45]
	global_store_dwordx4 v[44:45], v[8:11], off
	v_or_b32_e32 v12, s12, v27
	v_lshlrev_b32_e32 v12, 9, v12
	v_cvt_pk_bf16_f32 v8, v15, v13
	v_cvt_pk_bf16_f32 v9, v17, v19
	v_cvt_pk_bf16_f32 v10, v21, v23
	v_cvt_pk_bf16_f32 v11, v39, v41
	ds_read2_b32 v[14:15], v26 offset0:49 offset1:57
	ds_read2_b32 v[16:17], v26 offset0:16 offset1:24
	ds_read2_b32 v[18:19], v26 offset0:82 offset1:90
	ds_read2_b32 v[20:21], v26 offset0:115 offset1:123
	ds_read2_b32 v[22:23], v26 offset0:148 offset1:156
	ds_read2_b32 v[38:39], v26 offset0:181 offset1:189
	ds_read2_b32 v[40:41], v26 offset0:214 offset1:222
	ds_read2_b32 v[44:45], v26 offset0:247 offset1:255
	v_mov_b32_e32 v13, v1
	v_lshl_add_u64 v[12:13], v[42:43], 0, v[12:13]
	global_store_dwordx4 v[12:13], v[8:11], off
	v_or_b32_e32 v12, s12, v28
	v_lshlrev_b32_e32 v12, 9, v12
	v_mov_b32_e32 v13, v1
	s_waitcnt lgkmcnt(6)
	v_cvt_pk_bf16_f32 v8, v16, v14
	s_waitcnt lgkmcnt(4)
	v_cvt_pk_bf16_f32 v9, v18, v20
	s_waitcnt lgkmcnt(2)
	v_cvt_pk_bf16_f32 v10, v22, v38
	s_waitcnt lgkmcnt(0)
	v_cvt_pk_bf16_f32 v11, v40, v44
	v_lshl_add_u64 v[12:13], v[42:43], 0, v[12:13]
	global_store_dwordx4 v[12:13], v[8:11], off
	v_or_b32_e32 v12, s12, v29
	v_lshlrev_b32_e32 v12, 9, v12
	v_mov_b32_e32 v13, v1
	v_cvt_pk_bf16_f32 v8, v17, v15
	v_cvt_pk_bf16_f32 v9, v19, v21
	v_cvt_pk_bf16_f32 v10, v23, v39
	v_cvt_pk_bf16_f32 v11, v41, v45
	v_lshl_add_u64 v[12:13], v[42:43], 0, v[12:13]
	global_store_dwordx4 v[12:13], v[8:11], off
	s_waitcnt lgkmcnt(0)
	s_mov_b64 s[12:13], 0
.LBB0_2100:
	s_and_b64 vcc, exec, s[12:13]
	s_cbranch_vccz .LBB0_2095
	s_ashr_i32 s8, s33, 31
	s_lshr_b32 s8, s8, 27
	s_add_i32 s8, s33, s8
	s_load_dwordx2 s[20:21], s[0:1], 0x30
	s_and_b32 s12, s8, 0x7ffffe0
	s_sub_i32 s12, s33, s12
	s_lshl_b32 s12, s12, 5
	s_lshl_b32 s8, s8, 1
	s_ashr_i32 s13, s12, 31
	s_and_b32 s14, s8, 0xffffffc0
	s_lshl_b64 s[22:23], s[12:13], 2
	s_waitcnt lgkmcnt(0)
	s_add_u32 s20, s20, s22
	s_addc_u32 s21, s21, s23
	v_lshl_add_u64 v[8:9], s[20:21], 0, v[0:1]
	v_lshl_add_u64 v[8:9], v[8:9], 0, s[10:11]
	v_or_b32_e32 v10, s14, v24
	s_mov_b32 s8, 0
	v_mov_b32_e32 v11, v30
	v_mov_b32_e32 v230, v10
	v_mov_b32_e32 v231, 0
	v_lshl_add_u64 v[232:233], v[230:231], 2, s[4:5]
	v_lshlrev_b64 v[230:231], 12, v[230:231]
	v_lshl_add_u64 v[230:231], v[8:9], 0, v[230:231]
	v_mov_b32_e32 v234, v11
	s_mov_b32 s62, 0x2000
	s_mov_b32 s63, 0
	global_load_dword v150, v[230:231], off nt
	v_lshl_add_u64 v[230:231], v[230:231], 0, s[62:63]
	global_load_dword v151, v[230:231], off nt
	v_lshl_add_u64 v[230:231], v[230:231], 0, s[62:63]
	global_load_dword v152, v[230:231], off nt
	v_lshl_add_u64 v[230:231], v[230:231], 0, s[62:63]
	global_load_dword v153, v[230:231], off nt
	v_lshl_add_u64 v[230:231], v[230:231], 0, s[62:63]
	global_load_dword v154, v[230:231], off nt
	v_lshl_add_u64 v[230:231], v[230:231], 0, s[62:63]
	global_load_dword v155, v[230:231], off nt
	v_lshl_add_u64 v[230:231], v[230:231], 0, s[62:63]
	global_load_dword v156, v[230:231], off nt
	v_lshl_add_u64 v[230:231], v[230:231], 0, s[62:63]
	global_load_dword v157, v[230:231], off nt
	v_lshl_add_u64 v[230:231], v[230:231], 0, s[62:63]
	global_load_dword v158, v[230:231], off nt
	v_lshl_add_u64 v[230:231], v[230:231], 0, s[62:63]
	global_load_dword v159, v[230:231], off nt
	v_lshl_add_u64 v[230:231], v[230:231], 0, s[62:63]
	global_load_dword v160, v[230:231], off nt
	v_lshl_add_u64 v[230:231], v[230:231], 0, s[62:63]
	global_load_dword v161, v[230:231], off nt
	v_lshl_add_u64 v[230:231], v[230:231], 0, s[62:63]
	global_load_dword v162, v[230:231], off nt
	v_lshl_add_u64 v[230:231], v[230:231], 0, s[62:63]
	global_load_dword v163, v[230:231], off nt
	v_lshl_add_u64 v[230:231], v[230:231], 0, s[62:63]
	global_load_dword v164, v[230:231], off nt
	v_lshl_add_u64 v[230:231], v[230:231], 0, s[62:63]
	global_load_dword v165, v[230:231], off nt
	v_lshl_add_u64 v[230:231], v[230:231], 0, s[62:63]
	global_load_dword v166, v[230:231], off nt
	v_lshl_add_u64 v[230:231], v[230:231], 0, s[62:63]
	global_load_dword v167, v[230:231], off nt
	v_lshl_add_u64 v[230:231], v[230:231], 0, s[62:63]
	global_load_dword v168, v[230:231], off nt
	v_lshl_add_u64 v[230:231], v[230:231], 0, s[62:63]
	global_load_dword v169, v[230:231], off nt
	v_lshl_add_u64 v[230:231], v[230:231], 0, s[62:63]
	global_load_dword v170, v[230:231], off nt
	v_lshl_add_u64 v[230:231], v[230:231], 0, s[62:63]
	global_load_dword v171, v[230:231], off nt
	v_lshl_add_u64 v[230:231], v[230:231], 0, s[62:63]
	global_load_dword v172, v[230:231], off nt
	v_lshl_add_u64 v[230:231], v[230:231], 0, s[62:63]
	global_load_dword v173, v[230:231], off nt
	v_lshl_add_u64 v[230:231], v[230:231], 0, s[62:63]
	global_load_dword v174, v[230:231], off nt
	v_lshl_add_u64 v[230:231], v[230:231], 0, s[62:63]
	global_load_dword v175, v[230:231], off nt
	v_lshl_add_u64 v[230:231], v[230:231], 0, s[62:63]
	global_load_dword v176, v[230:231], off nt
	v_lshl_add_u64 v[230:231], v[230:231], 0, s[62:63]
	global_load_dword v177, v[230:231], off nt
	v_lshl_add_u64 v[230:231], v[230:231], 0, s[62:63]
	global_load_dword v178, v[230:231], off nt
	v_lshl_add_u64 v[230:231], v[230:231], 0, s[62:63]
	global_load_dword v179, v[230:231], off nt
	v_lshl_add_u64 v[230:231], v[230:231], 0, s[62:63]
	global_load_dword v180, v[230:231], off nt
	v_lshl_add_u64 v[230:231], v[230:231], 0, s[62:63]
	global_load_dword v181, v[230:231], off nt
	global_load_dword v182, v[232:233], off
	global_load_dword v183, v[232:233], off offset:8
	global_load_dword v184, v[232:233], off offset:16
	global_load_dword v185, v[232:233], off offset:24
	global_load_dword v186, v[232:233], off offset:32
	global_load_dword v187, v[232:233], off offset:40
	global_load_dword v188, v[232:233], off offset:48
	global_load_dword v189, v[232:233], off offset:56
	global_load_dword v190, v[232:233], off offset:64
	global_load_dword v191, v[232:233], off offset:72
	global_load_dword v192, v[232:233], off offset:80
	global_load_dword v193, v[232:233], off offset:88
	global_load_dword v194, v[232:233], off offset:96
	global_load_dword v195, v[232:233], off offset:104
	global_load_dword v196, v[232:233], off offset:112
	global_load_dword v197, v[232:233], off offset:120
	s_waitcnt vmcnt(15)
	v_mul_f32_e32 v150, v150, v182
	ds_write_b32 v234, v150
	s_waitcnt vmcnt(14)
	v_mul_f32_e32 v151, v151, v183
	ds_write_b32 v234, v151 offset:264
	s_waitcnt vmcnt(13)
	v_mul_f32_e32 v152, v152, v184
	ds_write_b32 v234, v152 offset:528
	s_waitcnt vmcnt(12)
	v_mul_f32_e32 v153, v153, v185
	ds_write_b32 v234, v153 offset:792
	s_waitcnt vmcnt(11)
	v_mul_f32_e32 v154, v154, v186
	ds_write_b32 v234, v154 offset:1056
	s_waitcnt vmcnt(10)
	v_mul_f32_e32 v155, v155, v187
	ds_write_b32 v234, v155 offset:1320
	s_waitcnt vmcnt(9)
	v_mul_f32_e32 v156, v156, v188
	ds_write_b32 v234, v156 offset:1584
	s_waitcnt vmcnt(8)
	v_mul_f32_e32 v157, v157, v189
	ds_write_b32 v234, v157 offset:1848
	s_waitcnt vmcnt(7)
	v_mul_f32_e32 v158, v158, v190
	ds_write_b32 v234, v158 offset:2112
	s_waitcnt vmcnt(6)
	v_mul_f32_e32 v159, v159, v191
	ds_write_b32 v234, v159 offset:2376
	s_waitcnt vmcnt(5)
	v_mul_f32_e32 v160, v160, v192
	ds_write_b32 v234, v160 offset:2640
	s_waitcnt vmcnt(4)
	v_mul_f32_e32 v161, v161, v193
	ds_write_b32 v234, v161 offset:2904
	s_waitcnt vmcnt(3)
	v_mul_f32_e32 v162, v162, v194
	ds_write_b32 v234, v162 offset:3168
	s_waitcnt vmcnt(2)
	v_mul_f32_e32 v163, v163, v195
	ds_write_b32 v234, v163 offset:3432
	s_waitcnt vmcnt(1)
	v_mul_f32_e32 v164, v164, v196
	ds_write_b32 v234, v164 offset:3696
	s_waitcnt vmcnt(0)
	v_mul_f32_e32 v165, v165, v197
	ds_write_b32 v234, v165 offset:3960
	global_load_dword v182, v[232:233], off offset:128
	global_load_dword v183, v[232:233], off offset:136
	global_load_dword v184, v[232:233], off offset:144
	global_load_dword v185, v[232:233], off offset:152
	global_load_dword v186, v[232:233], off offset:160
	global_load_dword v187, v[232:233], off offset:168
	global_load_dword v188, v[232:233], off offset:176
	global_load_dword v189, v[232:233], off offset:184
	global_load_dword v190, v[232:233], off offset:192
	global_load_dword v191, v[232:233], off offset:200
	global_load_dword v192, v[232:233], off offset:208
	global_load_dword v193, v[232:233], off offset:216
	global_load_dword v194, v[232:233], off offset:224
	global_load_dword v195, v[232:233], off offset:232
	global_load_dword v196, v[232:233], off offset:240
	global_load_dword v197, v[232:233], off offset:248
	s_waitcnt vmcnt(15)
	v_mul_f32_e32 v166, v166, v182
	ds_write_b32 v234, v166 offset:4224
	s_waitcnt vmcnt(14)
	v_mul_f32_e32 v167, v167, v183
	ds_write_b32 v234, v167 offset:4488
	s_waitcnt vmcnt(13)
	v_mul_f32_e32 v168, v168, v184
	ds_write_b32 v234, v168 offset:4752
	s_waitcnt vmcnt(12)
	v_mul_f32_e32 v169, v169, v185
	ds_write_b32 v234, v169 offset:5016
	s_waitcnt vmcnt(11)
	v_mul_f32_e32 v170, v170, v186
	ds_write_b32 v234, v170 offset:5280
	s_waitcnt vmcnt(10)
	v_mul_f32_e32 v171, v171, v187
	ds_write_b32 v234, v171 offset:5544
	s_waitcnt vmcnt(9)
	v_mul_f32_e32 v172, v172, v188
	ds_write_b32 v234, v172 offset:5808
	s_waitcnt vmcnt(8)
	v_mul_f32_e32 v173, v173, v189
	ds_write_b32 v234, v173 offset:6072
	s_waitcnt vmcnt(7)
	v_mul_f32_e32 v174, v174, v190
	ds_write_b32 v234, v174 offset:6336
	s_waitcnt vmcnt(6)
	v_mul_f32_e32 v175, v175, v191
	ds_write_b32 v234, v175 offset:6600
	s_waitcnt vmcnt(5)
	v_mul_f32_e32 v176, v176, v192
	ds_write_b32 v234, v176 offset:6864
	s_waitcnt vmcnt(4)
	v_mul_f32_e32 v177, v177, v193
	ds_write_b32 v234, v177 offset:7128
	s_waitcnt vmcnt(3)
	v_mul_f32_e32 v178, v178, v194
	ds_write_b32 v234, v178 offset:7392
	s_waitcnt vmcnt(2)
	v_mul_f32_e32 v179, v179, v195
	ds_write_b32 v234, v179 offset:7656
	s_waitcnt vmcnt(1)
	v_mul_f32_e32 v180, v180, v196
	ds_write_b32 v234, v180 offset:7920
	s_waitcnt vmcnt(0)
	v_mul_f32_e32 v181, v181, v197
	ds_write_b32 v234, v181 offset:8184
	s_mov_b32 s8, 0x40
	v_add_u32_e32 v11, 0x2100, v11
	s_waitcnt lgkmcnt(0)
	ds_read2_b32 v[12:13], v26 offset0:33 offset1:41
	ds_read2_b32 v[14:15], v26 offset1:8
	ds_read2_b32 v[16:17], v26 offset0:66 offset1:74
	ds_read2_b32 v[18:19], v26 offset0:99 offset1:107
	ds_read2_b32 v[20:21], v26 offset0:132 offset1:140
	ds_read2_b32 v[22:23], v26 offset0:165 offset1:173
	ds_read2_b32 v[38:39], v26 offset0:198 offset1:206
	ds_read2_b32 v[40:41], v26 offset0:231 offset1:239
	v_or_b32_e32 v44, s12, v25
	s_ashr_i32 s15, s14, 31
	v_ashrrev_i32_e32 v45, 31, v44
	v_lshl_add_u64 v[42:43], s[14:15], 1, v[4:5]
	v_lshlrev_b64 v[44:45], 11, v[44:45]
	s_waitcnt lgkmcnt(6)
	v_cvt_pk_bf16_f32 v8, v14, v12
	s_waitcnt lgkmcnt(4)
	v_cvt_pk_bf16_f32 v9, v16, v18
	s_waitcnt lgkmcnt(2)
	v_cvt_pk_bf16_f32 v10, v20, v22
	s_waitcnt lgkmcnt(0)
	v_cvt_pk_bf16_f32 v11, v38, v40
	v_lshl_add_u64 v[44:45], v[42:43], 0, v[44:45]
	v_or_b32_e32 v12, s12, v27
	global_store_dwordx4 v[44:45], v[8:11], off
	s_nop 1
	v_cvt_pk_bf16_f32 v8, v15, v13
	v_ashrrev_i32_e32 v13, 31, v12
	v_cvt_pk_bf16_f32 v9, v17, v19
	v_cvt_pk_bf16_f32 v10, v21, v23
	v_cvt_pk_bf16_f32 v11, v39, v41
	v_lshlrev_b64 v[12:13], 11, v[12:13]
	ds_read2_b32 v[14:15], v26 offset0:49 offset1:57
	ds_read2_b32 v[16:17], v26 offset0:16 offset1:24
	ds_read2_b32 v[18:19], v26 offset0:82 offset1:90
	ds_read2_b32 v[20:21], v26 offset0:115 offset1:123
	ds_read2_b32 v[22:23], v26 offset0:148 offset1:156
	ds_read2_b32 v[38:39], v26 offset0:181 offset1:189
	ds_read2_b32 v[40:41], v26 offset0:214 offset1:222
	ds_read2_b32 v[44:45], v26 offset0:247 offset1:255
	v_lshl_add_u64 v[12:13], v[42:43], 0, v[12:13]
	global_store_dwordx4 v[12:13], v[8:11], off
	v_or_b32_e32 v12, s12, v28
	v_ashrrev_i32_e32 v13, 31, v12
	v_lshlrev_b64 v[12:13], 11, v[12:13]
	s_waitcnt lgkmcnt(6)
	v_cvt_pk_bf16_f32 v8, v16, v14
	s_waitcnt lgkmcnt(4)
	v_cvt_pk_bf16_f32 v9, v18, v20
	s_waitcnt lgkmcnt(2)
	v_cvt_pk_bf16_f32 v10, v22, v38
	s_waitcnt lgkmcnt(0)
	v_cvt_pk_bf16_f32 v11, v40, v44
	v_lshl_add_u64 v[12:13], v[42:43], 0, v[12:13]
	global_store_dwordx4 v[12:13], v[8:11], off
	v_or_b32_e32 v12, s12, v29
	v_ashrrev_i32_e32 v13, 31, v12
	v_lshlrev_b64 v[12:13], 11, v[12:13]
	v_cvt_pk_bf16_f32 v8, v17, v15
	v_cvt_pk_bf16_f32 v9, v19, v21
	v_cvt_pk_bf16_f32 v10, v23, v39
	v_cvt_pk_bf16_f32 v11, v41, v45
	v_lshl_add_u64 v[12:13], v[42:43], 0, v[12:13]
	global_store_dwordx4 v[12:13], v[8:11], off
	s_waitcnt lgkmcnt(0)
	s_branch .LBB0_2095
